# v6 plus epilogue de-serialisation: in-proj row-scale reductions batch their 16 ds_bpermute round trips; RWKV producers drop four same-wave LDS write-to-read waits
# speedup vs baseline: 1.0094x; 1.0064x over previous
; #define LAS __attribute__((address_space(3)))
; __device__ __forceinline__ f32x4 bf4(v2u u) { return (f32x4){bflo(u.x), bfhi(u.x), bflo(u.y), bfhi(u.y)}; }
; __device__ __forceinline__ float row16_sum(float x) { x += dpp_f<0xB1>(x); x += dpp_f<0x4E>(x); x += dpp_f<0x141>(x); x += dpp_f<0x140>(x); return x; }
; __device__ __forceinline__ void rw_scan(const bf16* R, const bf16* K, const bf16* V, const bf16* WM, const bf16* A, const float* k_k, const float* k_a, bf16* Y, LAS unsigned char* lds) {
;     ...
;                     LAS unsigned char* slot = lds + (cj % RW_NSLOT) * RWS_SLOT;
;                     f32x4 wv[4], kk[4], km[4], be[4], rr[4];
; #pragma unroll
;                     for (int j = 0; j < 4; ++j) {
;                         const f32x4 r = bf4(cu.r[j]), k = bf4(cu.k[j]), wm = bf4(cu.wm[j]), a = bf4(cu.a[j]);
;                         const f32x4 kr = k * kkc;
;                         const float n2 = row16_sum((kr[0] * kr[0] + kr[1] * kr[1]) + (kr[2] * kr[2] + kr[3] * kr[3]));
;                         const float inv = 1.0f / fmaxf(sqrtf(n2), 1e-12f);
;                         kk[j] = kr * inv; be[j] = kk[j] * a; km[j] = k * (1.0f + (a - 1.0f) * kac); wv[j] = 1.0f - wm; rr[j] = r;
.LBB0_498:
	s_waitcnt vmcnt(21)
	v_lshlrev_b32_e32 v92, 16, v70
	v_and_b32_e32 v93, 0xffff0000, v70
	v_lshlrev_b32_e32 v94, 16, v71
	v_and_b32_e32 v95, 0xffff0000, v71
	v_pk_mul_f32 v[70:71], v[0:1], v[92:93]
	v_pk_mul_f32 v[72:73], v[2:3], v[94:95]
	v_lshlrev_b32_e32 v34, 16, v66
	v_and_b32_e32 v88, 0xffff0000, v66
	v_lshlrev_b32_e32 v89, 16, v67
	v_and_b32_e32 v90, 0xffff0000, v67
	v_pk_mul_f32 v[66:67], v[72:73], v[72:73]
	v_pk_mul_f32 v[82:83], v[70:71], v[70:71]
	v_sub_f32_e32 v103, 1.0, v90
	v_pk_mov_b32 v[86:87], v[82:83], v[66:67] op_sel:[1,0]
	v_mov_b32_e32 v83, v67
	v_pk_add_f32 v[66:67], v[86:87], v[82:83]
	v_lshlrev_b32_e32 v82, 16, v80
	v_and_b32_e32 v83, 0xffff0000, v80
	v_lshlrev_b32_e32 v90, 16, v81
	v_and_b32_e32 v91, 0xffff0000, v81
	v_lshlrev_b32_e32 v112, 16, v78
	v_and_b32_e32 v113, 0xffff0000, v78
	v_lshlrev_b32_e32 v114, 16, v79
	v_and_b32_e32 v115, 0xffff0000, v79
	v_pk_mul_f32 v[78:79], v[0:1], v[82:83]
	v_pk_mul_f32 v[80:81], v[2:3], v[90:91]
	v_sub_f32_e32 v101, 1.0, v88
	v_sub_f32_e32 v102, 1.0, v89
	v_pk_mul_f32 v[86:87], v[80:81], v[80:81]
	v_pk_mul_f32 v[88:89], v[78:79], v[78:79]
	v_sub_f32_e32 v100, 1.0, v34
	v_pk_mov_b32 v[110:111], v[88:89], v[86:87] op_sel:[1,0]
	v_mov_b32_e32 v89, v87
	v_pk_add_f32 v[86:87], v[110:111], v[88:89]
	s_mul_hi_u32 s68, s89, 0x38e38e39
	v_add_f32_e32 v34, v86, v87
	s_lshr_b32 s68, s68, 1
	s_mul_i32 s68, s68, 9
	v_add_f32_dpp v34, v34, v34 quad_perm:[1,0,3,2] row_mask:0xf bank_mask:0xf bound_ctrl:1
	s_sub_i32 s92, s89, s68
	v_lshlrev_b32_e32 v108, 16, v74
	v_add_f32_dpp v34, v34, v34 quad_perm:[2,3,0,1] row_mask:0xf bank_mask:0xf bound_ctrl:1
	v_and_b32_e32 v109, 0xffff0000, v74
	v_and_b32_e32 v111, 0xffff0000, v107
	v_add_f32_dpp v34, v34, v34 row_half_mirror row_mask:0xf bank_mask:0xf bound_ctrl:1
	v_lshlrev_b32_e32 v120, 16, v104
	v_and_b32_e32 v121, 0xffff0000, v104
	v_add_f32_dpp v34, v34, v34 row_mirror row_mask:0xf bank_mask:0xf bound_ctrl:1
	v_cmp_gt_f32_e32 vcc, s24, v34
	v_mul_f32_e32 v86, 0x4f800000, v34
	v_lshlrev_b32_e32 v122, 16, v105
	v_cndmask_b32_e32 v34, v34, v86, vcc
	v_sqrt_f32_e32 v86, v34
	v_and_b32_e32 v123, 0xffff0000, v105
	v_sub_f32_e32 v127, 1.0, v113
	v_sub_f32_e32 v126, 1.0, v112
	v_add_u32_e32 v87, -1, v86
	v_fma_f32 v88, -v87, v86, v34
	v_cmp_ge_f32_e64 s[68:69], 0, v88
	v_add_u32_e32 v88, 1, v86
	v_sub_f32_e32 v129, 1.0, v115
	v_cndmask_b32_e64 v87, v86, v87, s[68:69]
	v_fma_f32 v86, -v88, v86, v34
	v_cmp_lt_f32_e64 s[68:69], 0, v86
	v_sub_f32_e32 v128, 1.0, v114
	v_lshlrev_b32_e32 v116, 16, v98
	v_cndmask_b32_e64 v86, v87, v88, s[68:69]
	v_mul_f32_e32 v87, 0x37800000, v86
	v_cndmask_b32_e32 v86, v86, v87, vcc
	v_cmp_class_f32_e32 vcc, v34, v229
	v_and_b32_e32 v117, 0xffff0000, v98
	v_sub_f32_e32 v133, 1.0, v121
	v_cndmask_b32_e32 v34, v86, v34, vcc
	v_max_f32_e32 v34, 0x2b8cbccc, v34
	v_div_scale_f32 v86, s[68:69], v34, v34, 1.0
	v_rcp_f32_e32 v87, v86
	v_sub_f32_e32 v132, 1.0, v120
	v_lshlrev_b32_e32 v120, 16, v85
	v_and_b32_e32 v121, 0xffff0000, v85
	v_fma_f32 v88, -v86, v87, 1.0
	v_fmac_f32_e32 v87, v88, v87
	v_div_scale_f32 v88, vcc, 1.0, v34, 1.0
	v_mul_f32_e32 v89, v88, v87
	v_fma_f32 v110, -v86, v89, v88
	v_fmac_f32_e32 v89, v110, v87
	v_fma_f32 v86, -v86, v89, v88
	v_div_fmas_f32 v86, v86, v87, v89
	v_div_fixup_f32 v34, v86, v34, 1.0
	v_pk_mul_f32 v[88:89], v[78:79], v[34:35] op_sel_hi:[1,0]
	v_lshlrev_b32_e32 v110, 16, v107
	v_pk_mul_f32 v[78:79], v[88:89], v[108:109]
	v_pk_add_f32 v[108:109], v[108:109], -1.0 op_sel_hi:[1,0]
	v_pk_mul_f32 v[86:87], v[80:81], v[34:35] op_sel_hi:[1,0]
	v_pk_fma_f32 v[108:109], v[4:5], v[108:109], 1.0 op_sel_hi:[1,1,0]
	v_sub_f32_e32 v131, 1.0, v123
	v_pk_mul_f32 v[82:83], v[108:109], v[82:83]
	v_lshlrev_b32_e32 v108, 16, v106
	v_and_b32_e32 v109, 0xffff0000, v106
	v_pk_mul_f32 v[104:105], v[0:1], v[108:109]
	v_pk_mul_f32 v[106:107], v[2:3], v[110:111]
	v_pk_mul_f32 v[114:115], v[104:105], v[104:105]
	v_pk_mul_f32 v[112:113], v[106:107], v[106:107]
	v_sub_f32_e32 v130, 1.0, v122
	v_pk_mov_b32 v[118:119], v[114:115], v[112:113] op_sel:[1,0]
	v_mov_b32_e32 v115, v113
	v_pk_add_f32 v[112:113], v[118:119], v[114:115]
	v_and_b32_e32 v119, 0xffff0000, v84
	v_add_f32_e32 v34, v112, v113
	v_lshlrev_b32_e32 v136, 16, v10
	v_and_b32_e32 v137, 0xffff0000, v10
	v_add_f32_dpp v34, v34, v34 quad_perm:[1,0,3,2] row_mask:0xf bank_mask:0xf bound_ctrl:1
	v_lshlrev_b32_e32 v164, 16, v11
	v_and_b32_e32 v165, 0xffff0000, v11
	v_add_f32_dpp v34, v34, v34 quad_perm:[2,3,0,1] row_mask:0xf bank_mask:0xf bound_ctrl:1
	v_lshlrev_b32_e32 v10, 16, v8
	v_and_b32_e32 v11, 0xffff0000, v8
	v_add_f32_dpp v34, v34, v34 row_half_mirror row_mask:0xf bank_mask:0xf bound_ctrl:1
	v_lshlrev_b32_e32 v8, 16, v9
	v_and_b32_e32 v9, 0xffff0000, v9
	v_add_f32_dpp v34, v34, v34 row_mirror row_mask:0xf bank_mask:0xf bound_ctrl:1
	v_cmp_gt_f32_e32 vcc, s24, v34
	v_mul_f32_e32 v112, 0x4f800000, v34
	v_pk_mul_f32 v[166:167], v[100:101], v[126:127]
	v_cndmask_b32_e32 v34, v34, v112, vcc
	v_sqrt_f32_e32 v112, v34
	v_pk_mul_f32 v[132:133], v[166:167], v[132:133]
	v_add_f32_e32 v66, v66, v67
	s_mul_i32 s74, s92, 0x2c00
	v_add_u32_e32 v113, -1, v112
	v_fma_f32 v114, -v113, v112, v34
	v_cmp_ge_f32_e64 s[68:69], 0, v114
	v_add_u32_e32 v114, 1, v112
	v_add_f32_dpp v66, v66, v66 quad_perm:[1,0,3,2] row_mask:0xf bank_mask:0xf bound_ctrl:1
	v_cndmask_b32_e64 v113, v112, v113, s[68:69]
	v_fma_f32 v112, -v114, v112, v34
	v_cmp_lt_f32_e64 s[68:69], 0, v112
	v_add_f32_dpp v66, v66, v66 quad_perm:[2,3,0,1] row_mask:0xf bank_mask:0xf bound_ctrl:1
	s_waitcnt vmcnt(20)
; __device__ __forceinline__ f32x4 bf4(v2u u) { return (f32x4){bflo(u.x), bfhi(u.x), bflo(u.y), bfhi(u.y)}; }
; __device__ __forceinline__ float row16_sum(float x) { x += dpp_f<0xB1>(x); x += dpp_f<0x4E>(x); x += dpp_f<0x141>(x); x += dpp_f<0x140>(x); return x; }
; __device__ __forceinline__ void rw_scan(const bf16* R, const bf16* K, const bf16* V, const bf16* WM, const bf16* A, const float* k_k, const float* k_a, bf16* Y, LAS unsigned char* lds) {
;     ...
;                     for (int j = 0; j < 4; ++j) {
;                         const f32x4 r = bf4(cu.r[j]), k = bf4(cu.k[j]), wm = bf4(cu.wm[j]), a = bf4(cu.a[j]);
;                         const f32x4 kr = k * kkc;
;                         const float n2 = row16_sum((kr[0] * kr[0] + kr[1] * kr[1]) + (kr[2] * kr[2] + kr[3] * kr[3]));
;                         const float inv = 1.0f / fmaxf(sqrtf(n2), 1e-12f);
;                         kk[j] = kr * inv; be[j] = kk[j] * a; km[j] = k * (1.0f + (a - 1.0f) * kac); wv[j] = 1.0f - wm; rr[j] = r;
;                     }
;                     f32x4 g[4]; g[0] = wv[0]; g[1] = g[0] * wv[1]; g[2] = g[1] * wv[2]; g[3] = g[2] * wv[3];
;                     f32x4 pre = (f32x4){1.f, 1.f, 1.f, 1.f}, all = (f32x4){1.f, 1.f, 1.f, 1.f};
; #pragma unroll
;                     for (int x = 0; x < 4; ++x) {
;                         const float t0 = __shfl(g[3][x], fr), t1 = __shfl(g[3][x], 16 + fr), t2 = __shfl(g[3][x], 32 + fr), t3 = __shfl(g[3][x], 48 + fr);
;                         float p = 1.f; if (fq > 0) p *= t0; if (fq > 1) p *= t1; if (fq > 2) p *= t2;
;                         pre[x] = p; all[x] = (t0 * t1) * (t2 * t3);
;                     }
	v_and_b32_e32 v175, 0xffff0000, v33
	v_cndmask_b32_e64 v112, v113, v114, s[68:69]
	v_mul_f32_e32 v113, 0x37800000, v112
	v_cndmask_b32_e32 v112, v112, v113, vcc
	v_cmp_class_f32_e32 vcc, v34, v229
	v_add_f32_dpp v202, v66, v66 row_half_mirror row_mask:0xf bank_mask:0xf bound_ctrl:1
	s_add_i32 s74, s74, 0
	v_cndmask_b32_e32 v34, v112, v34, vcc
	v_max_f32_e32 v34, 0x2b8cbccc, v34
	v_div_scale_f32 v112, s[68:69], v34, v34, 1.0
	v_rcp_f32_e32 v113, v112
	v_mov_b32_dpp v203, v202 row_mirror row_mask:0xf bank_mask:0xf bound_ctrl:1
	v_add_u32_e32 v204, s74, v146
	v_fma_f32 v114, -v112, v113, 1.0
	v_fmac_f32_e32 v113, v114, v113
	v_div_scale_f32 v114, vcc, 1.0, v34, 1.0
	v_mul_f32_e32 v115, v114, v113
	v_fma_f32 v118, -v112, v115, v114
	v_fmac_f32_e32 v115, v118, v113
	v_fma_f32 v112, -v112, v115, v114
	v_div_fmas_f32 v112, v112, v113, v115
	v_div_fixup_f32 v34, v112, v34, 1.0
	v_pk_mul_f32 v[114:115], v[104:105], v[34:35] op_sel_hi:[1,0]
	v_lshlrev_b32_e32 v118, 16, v84
	v_pk_mul_f32 v[104:105], v[114:115], v[116:117]
	v_pk_add_f32 v[116:117], v[116:117], -1.0 op_sel_hi:[1,0]
	v_pk_mul_f32 v[84:85], v[0:1], v[118:119]
	v_pk_fma_f32 v[116:117], v[4:5], v[116:117], 1.0 op_sel_hi:[1,1,0]
	v_pk_mul_f32 v[124:125], v[84:85], v[84:85]
	v_pk_mul_f32 v[108:109], v[116:117], v[108:109]
	v_pk_mul_f32 v[116:117], v[2:3], v[120:121]
	v_pk_mul_f32 v[112:113], v[106:107], v[34:35] op_sel_hi:[1,0]
	v_pk_mul_f32 v[122:123], v[116:117], v[116:117]
	v_lshlrev_b32_e32 v74, 16, v75
	v_pk_mov_b32 v[134:135], v[124:125], v[122:123] op_sel:[1,0]
	v_mov_b32_e32 v125, v123
	v_pk_add_f32 v[122:123], v[134:135], v[124:125]
	v_and_b32_e32 v75, 0xffff0000, v75
	v_add_f32_e32 v34, v122, v123
	v_pk_mul_f32 v[80:81], v[86:87], v[74:75]
	v_pk_add_f32 v[74:75], v[74:75], -1.0 op_sel_hi:[1,0]
	v_add_f32_dpp v34, v34, v34 quad_perm:[1,0,3,2] row_mask:0xf bank_mask:0xf bound_ctrl:1
	v_pk_fma_f32 v[74:75], v[6:7], v[74:75], 1.0 op_sel_hi:[1,1,0]
	v_lshlrev_b32_e32 v66, 16, v68
	v_add_f32_dpp v34, v34, v34 quad_perm:[2,3,0,1] row_mask:0xf bank_mask:0xf bound_ctrl:1
	v_pk_mul_f32 v[90:91], v[74:75], v[90:91]
	v_and_b32_e32 v67, 0xffff0000, v68
	v_add_f32_dpp v34, v34, v34 row_half_mirror row_mask:0xf bank_mask:0xf bound_ctrl:1
	v_lshlrev_b32_e32 v68, 16, v69
	v_and_b32_e32 v69, 0xffff0000, v69
	v_add_f32_dpp v34, v34, v34 row_mirror row_mask:0xf bank_mask:0xf bound_ctrl:1
	v_cmp_gt_f32_e32 vcc, s24, v34
	v_mul_f32_e32 v122, 0x4f800000, v34
	v_lshlrev_b32_e32 v98, 16, v99
	v_cndmask_b32_e32 v34, v34, v122, vcc
	v_sqrt_f32_e32 v122, v34
	v_and_b32_e32 v99, 0xffff0000, v99
	v_pk_mul_f32 v[106:107], v[112:113], v[98:99]
	v_pk_add_f32 v[98:99], v[98:99], -1.0 op_sel_hi:[1,0]
	v_add_u32_e32 v123, -1, v122
	v_fma_f32 v124, -v123, v122, v34
	v_cmp_ge_f32_e64 s[68:69], 0, v124
	v_add_u32_e32 v124, 1, v122
	v_pk_fma_f32 v[98:99], v[6:7], v[98:99], 1.0 op_sel_hi:[1,1,0]
	v_cndmask_b32_e64 v123, v122, v123, s[68:69]
	v_fma_f32 v122, -v124, v122, v34
	v_cmp_lt_f32_e64 s[68:69], 0, v122
	v_pk_mul_f32 v[110:111], v[98:99], v[110:111]
	v_lshlrev_b32_e32 v74, 16, v76
	v_cndmask_b32_e64 v122, v123, v124, s[68:69]
	v_mul_f32_e32 v123, 0x37800000, v122
	v_cndmask_b32_e32 v122, v122, v123, vcc
	v_cmp_class_f32_e32 vcc, v34, v229
	v_and_b32_e32 v75, 0xffff0000, v76
	v_lshlrev_b32_e32 v76, 16, v77
	v_cndmask_b32_e32 v34, v122, v34, vcc
	v_max_f32_e32 v34, 0x2b8cbccc, v34
	v_div_scale_f32 v122, s[68:69], v34, v34, 1.0
	v_rcp_f32_e32 v123, v122
	v_and_b32_e32 v77, 0xffff0000, v77
	v_lshlrev_b32_e32 v98, 16, v96
	v_and_b32_e32 v99, 0xffff0000, v96
	v_fma_f32 v124, -v122, v123, 1.0
	v_fmac_f32_e32 v123, v124, v123
	v_div_scale_f32 v124, vcc, 1.0, v34, 1.0
	v_mul_f32_e32 v125, v124, v123
	v_fma_f32 v134, -v122, v125, v124
	v_fmac_f32_e32 v125, v134, v123
	v_fma_f32 v122, -v122, v125, v124
	v_div_fmas_f32 v122, v122, v123, v125
	v_div_fixup_f32 v34, v122, v34, 1.0
	v_pk_mul_f32 v[122:123], v[116:117], v[34:35] op_sel_hi:[1,0]
	v_pk_mul_f32 v[124:125], v[84:85], v[34:35] op_sel_hi:[1,0]
	v_pk_mul_f32 v[116:117], v[122:123], v[8:9]
	v_pk_add_f32 v[8:9], v[8:9], -1.0 op_sel_hi:[1,0]
	v_pk_mul_f32 v[84:85], v[124:125], v[10:11]
	v_pk_add_f32 v[10:11], v[10:11], -1.0 op_sel_hi:[1,0]
	v_pk_fma_f32 v[8:9], v[6:7], v[8:9], 1.0 op_sel_hi:[1,1,0]
	v_pk_fma_f32 v[10:11], v[4:5], v[10:11], 1.0 op_sel_hi:[1,1,0]
	v_pk_mul_f32 v[120:121], v[8:9], v[120:121]
	v_sub_f32_e32 v9, 1.0, v137
	v_sub_f32_e32 v8, 1.0, v136
	v_pk_mul_f32 v[118:119], v[10:11], v[118:119]
	v_sub_f32_e32 v11, 1.0, v165
	v_sub_f32_e32 v10, 1.0, v164
	v_pk_mul_f32 v[164:165], v[102:103], v[128:129]
	v_pk_mul_f32 v[128:129], v[132:133], v[8:9]
	v_or_b32_e32 v8, v232, v24
	v_lshlrev_b32_e32 v34, 2, v8
	v_or_b32_e32 v8, v232, v143
	v_lshlrev_b32_e32 v171, 2, v8
	v_or_b32_e32 v8, v232, v144
	v_lshlrev_b32_e32 v173, 2, v8
	v_or_b32_e32 v8, v232, v145
	v_pk_mul_f32 v[134:135], v[164:165], v[130:131]
	v_lshlrev_b32_e32 v174, 2, v8
	ds_bpermute_b32 v8, v34, v128
	v_pk_mul_f32 v[126:127], v[134:135], v[10:11]
	ds_bpermute_b32 v10, v171, v128
	ds_bpermute_b32 v136, v173, v128
	ds_bpermute_b32 v9, v34, v129
	ds_bpermute_b32 v168, v174, v128
	ds_bpermute_b32 v11, v171, v129
	ds_bpermute_b32 v169, v173, v129
	ds_bpermute_b32 v137, v174, v129
	s_waitcnt lgkmcnt(7)
	v_cndmask_b32_e64 v130, v8, 1.0, s[42:43]
	s_waitcnt lgkmcnt(6)
	v_mul_f32_e32 v131, v130, v10
	v_cndmask_b32_e64 v130, v130, v131, s[44:45]
	s_waitcnt lgkmcnt(5)
	v_mul_f32_e32 v131, v130, v136
	v_cndmask_b32_e64 v130, v130, v131, s[46:47]
	s_waitcnt lgkmcnt(4)
	v_cndmask_b32_e64 v131, v9, 1.0, s[42:43]
	s_waitcnt lgkmcnt(2)
	v_mul_f32_e32 v170, v131, v11
	v_pk_mul_f32 v[8:9], v[8:9], v[10:11]
	s_waitcnt lgkmcnt(0)
; #define LAS __attribute__((address_space(3)))
; __device__ __forceinline__ void rw_scan(const bf16* R, const bf16* K, const bf16* V, const bf16* WM, const bf16* A, const float* k_k, const float* k_a, bf16* Y, LAS unsigned char* lds) {
;     ...
;                         const f32x4 r = bf4(cu.r[j]), k = bf4(cu.k[j]), wm = bf4(cu.wm[j]), a = bf4(cu.a[j]);
;                         const f32x4 kr = k * kkc;
;                         const float n2 = row16_sum((kr[0] * kr[0] + kr[1] * kr[1]) + (kr[2] * kr[2] + kr[3] * kr[3]));
;                         const float inv = 1.0f / fmaxf(sqrtf(n2), 1e-12f);
;                         kk[j] = kr * inv; be[j] = kk[j] * a; km[j] = k * (1.0f + (a - 1.0f) * kac); wv[j] = 1.0f - wm; rr[j] = r;
;                     }
;                     f32x4 g[4]; g[0] = wv[0]; g[1] = g[0] * wv[1]; g[2] = g[1] * wv[2]; g[3] = g[2] * wv[3];
;                     f32x4 pre = (f32x4){1.f, 1.f, 1.f, 1.f}, all = (f32x4){1.f, 1.f, 1.f, 1.f};
; #pragma unroll
;                     for (int x = 0; x < 4; ++x) {
;                         const float t0 = __shfl(g[3][x], fr), t1 = __shfl(g[3][x], 16 + fr), t2 = __shfl(g[3][x], 32 + fr), t3 = __shfl(g[3][x], 48 + fr);
;                         float p = 1.f; if (fq > 0) p *= t0; if (fq > 1) p *= t1; if (fq > 2) p *= t2;
;                         pre[x] = p; all[x] = (t0 * t1) * (t2 * t3);
;                     }
;                     unsigned kgp[4][2], bgp[4][2], abp[4][2];
;                     float kgt[4][4], bgt[4][4], abt[4][4];
; #pragma unroll
;                     for (int j = 0; j < 4; ++j) {
;                         const f32x4 Gs = pre * g[j], Gm = j ? pre * g[j - 1] : pre;
;                         f32x4 ginv; ginv[0] = __builtin_amdgcn_rcpf(Gs[0]); ginv[1] = __builtin_amdgcn_rcpf(Gs[1]); ginv[2] = __builtin_amdgcn_rcpf(Gs[2]); ginv[3] = __builtin_amdgcn_rcpf(Gs[3]);
;                         const f32x4 alb = kk[j] * Gm, rb = rr[j] * Gs, bet = be[j] * ginv, ktl = km[j] * ginv;
;                         const int s = 4 * fq + j;
;                         v2u o;
;                         o.x = pk2(alb[0], alb[1]); o.y = pk2(alb[2], alb[3]); *(LAS v2u*)(tmp + RWT_AB + s * 128 + 8 * fr) = o;
;                         o.x = pk2(bet[0], bet[1]); o.y = pk2(bet[2], bet[3]); *(LAS v2u*)(tmp + RWT_BT + s * 128 + 8 * fr) = o;
	v_pk_mul_f32 v[10:11], v[168:169], v[136:137]
	v_cndmask_b32_e64 v131, v131, v170, s[44:45]
	v_pk_mul_f32 v[8:9], v[8:9], v[10:11]
	ds_bpermute_b32 v10, v34, v126
	ds_bpermute_b32 v168, v171, v126
	v_mul_f32_e32 v170, v131, v169
	v_cndmask_b32_e64 v131, v131, v170, s[46:47]
	ds_bpermute_b32 v170, v173, v126
	ds_bpermute_b32 v11, v34, v127
	ds_bpermute_b32 v172, v174, v126
	ds_bpermute_b32 v169, v171, v127
	ds_bpermute_b32 v173, v173, v127
	ds_bpermute_b32 v171, v174, v127
	s_waitcnt lgkmcnt(7)
	v_cndmask_b32_e64 v34, v10, 1.0, s[42:43]
	s_waitcnt lgkmcnt(6)
	v_mul_f32_e32 v136, v34, v168
	v_cndmask_b32_e64 v34, v34, v136, s[44:45]
	s_waitcnt lgkmcnt(5)
	v_mul_f32_e32 v136, v34, v170
	v_cndmask_b32_e64 v136, v34, v136, s[46:47]
	s_waitcnt lgkmcnt(4)
	v_cndmask_b32_e64 v34, v11, 1.0, s[42:43]
	s_waitcnt lgkmcnt(2)
	v_mul_f32_e32 v137, v34, v169
	v_pk_mul_f32 v[10:11], v[10:11], v[168:169]
	s_waitcnt lgkmcnt(0)
	v_pk_mul_f32 v[168:169], v[172:173], v[170:171]
	v_cndmask_b32_e64 v34, v34, v137, s[44:45]
	v_pk_mul_f32 v[10:11], v[10:11], v[168:169]
	v_lshlrev_b32_e32 v168, 16, v64
	v_and_b32_e32 v169, 0xffff0000, v64
	v_mul_f32_e32 v137, v34, v173
	v_pk_add_f32 v[170:171], v[168:169], -1.0 op_sel_hi:[1,0]
	v_cndmask_b32_e64 v137, v34, v137, s[46:47]
	v_pk_fma_f32 v[170:171], v[4:5], v[170:171], 1.0 op_sel_hi:[1,1,0]
	v_add_f32_e32 v34, v202, v203
	v_pk_mul_f32 v[92:93], v[170:171], v[92:93]
	v_cmp_gt_f32_e32 vcc, s24, v34
	v_mul_f32_e32 v170, 0x4f800000, v34
	v_lshlrev_b32_e32 v64, 16, v65
	v_cndmask_b32_e32 v34, v34, v170, vcc
	v_sqrt_f32_e32 v170, v34
	v_and_b32_e32 v65, 0xffff0000, v65
	v_pk_add_f32 v[172:173], v[64:65], -1.0 op_sel_hi:[1,0]
	v_pk_mul_f32 v[102:103], v[102:103], v[136:137]
	v_pk_fma_f32 v[172:173], v[6:7], v[172:173], 1.0 op_sel_hi:[1,1,0]
	v_add_u32_e32 v171, -1, v170
	v_pk_mul_f32 v[94:95], v[172:173], v[94:95]
	v_fma_f32 v172, -v171, v170, v34
	v_cmp_ge_f32_e64 s[68:69], 0, v172
	v_add_u32_e32 v172, 1, v170
	v_pk_mul_f32 v[100:101], v[100:101], v[130:131]
	v_cndmask_b32_e64 v171, v170, v171, s[68:69]
	v_fma_f32 v170, -v172, v170, v34
	v_cmp_lt_f32_e64 s[68:69], 0, v170
	v_rcp_f32_e32 v176, v100
	v_rcp_f32_e32 v177, v101
	v_cndmask_b32_e64 v170, v171, v172, s[68:69]
	v_mul_f32_e32 v171, 0x37800000, v170
	v_cndmask_b32_e32 v170, v170, v171, vcc
	v_cmp_class_f32_e32 vcc, v34, v229
	v_rcp_f32_e32 v178, v102
	v_rcp_f32_e32 v179, v103
	v_cndmask_b32_e32 v34, v170, v34, vcc
	v_max_f32_e32 v34, 0x2b8cbccc, v34
	v_div_scale_f32 v170, s[68:69], v34, v34, 1.0
	v_rcp_f32_e32 v171, v170
	v_pk_mul_f32 v[94:95], v[94:95], v[178:179]
	v_pk_mul_f32 v[92:93], v[92:93], v[176:177]
	v_pk_mul_f32 v[86:87], v[86:87], v[102:103]
	v_fma_f32 v172, -v170, v171, 1.0
	v_fmac_f32_e32 v171, v172, v171
	v_div_scale_f32 v172, vcc, 1.0, v34, 1.0
	v_mul_f32_e32 v173, v172, v171
	v_fma_f32 v174, -v170, v173, v172
	v_fmac_f32_e32 v173, v174, v171
	v_fma_f32 v170, -v170, v173, v172
	v_div_fmas_f32 v170, v170, v171, v173
	v_div_fixup_f32 v34, v170, v34, 1.0
	v_pk_mul_f32 v[72:73], v[72:73], v[34:35] op_sel_hi:[1,0]
	v_pk_mul_f32 v[70:71], v[70:71], v[34:35] op_sel_hi:[1,0]
	v_pk_mul_f32 v[170:171], v[72:73], v[64:65]
	v_pk_mul_f32 v[168:169], v[70:71], v[168:169]
	v_lshlrev_b32_e32 v172, 16, v32
	v_and_b32_e32 v173, 0xffff0000, v32
	v_lshlrev_b32_e32 v174, 16, v33
	v_pk_mul_f32 v[32:33], v[72:73], v[136:137]
	v_pk_mul_f32 v[64:65], v[70:71], v[130:131]
	v_pk_mul_f32 v[170:171], v[170:171], v[178:179]
	v_pk_mul_f32 v[168:169], v[168:169], v[176:177]
	v_pk_mul_f32 v[70:71], v[102:103], v[174:175]
	v_pk_mul_f32 v[72:73], v[100:101], v[172:173]
	v_cvt_pk_bf16_f32 v172, v64, v65
	v_cvt_pk_bf16_f32 v173, v32, v33
	v_add_u32_e32 v34, v147, v154
	v_cvt_pk_bf16_f32 v174, v168, v169
	v_cvt_pk_bf16_f32 v175, v170, v171
	ds_write2st64_b64 v34, v[172:173], v[174:175] offset1:4
	v_cvt_pk_bf16_f32 v172, v92, v93
	v_cvt_pk_bf16_f32 v173, v94, v95
	ds_write_b64 v34, v[172:173] offset:4096
	v_cvt_pk_bf16_f32 v72, v72, v73
	v_cvt_pk_bf16_f32 v73, v70, v71
	v_add_u32_e32 v34, v204, v154
	ds_write_b64 v34, v[72:73] offset:2048
	v_pk_mul_f32 v[70:71], v[164:165], v[136:137]
	v_pk_mul_f32 v[72:73], v[166:167], v[130:131]
	v_rcp_f32_e32 v166, v70
	v_rcp_f32_e32 v164, v72
	v_rcp_f32_e32 v165, v73
	v_rcp_f32_e32 v167, v71
	v_pk_mul_f32 v[88:89], v[88:89], v[100:101]
	v_cvt_pk_bf16_f32 v101, v86, v87
	v_pk_mul_f32 v[78:79], v[78:79], v[164:165]
	v_pk_mul_f32 v[80:81], v[80:81], v[166:167]
	v_pk_mul_f32 v[90:91], v[90:91], v[166:167]
	v_pk_mul_f32 v[82:83], v[82:83], v[164:165]
	v_cvt_pk_bf16_f32 v100, v88, v89
	v_add_u32_e32 v34, v147, v155
	v_cvt_pk_bf16_f32 v102, v78, v79
	v_cvt_pk_bf16_f32 v103, v80, v81
	v_pk_mul_f32 v[68:69], v[70:71], v[68:69]
	v_pk_mul_f32 v[66:67], v[72:73], v[66:67]
	ds_write2st64_b64 v34, v[100:101], v[102:103] offset1:4
	v_cvt_pk_bf16_f32 v100, v82, v83
	v_cvt_pk_bf16_f32 v101, v90, v91
	ds_write_b64 v34, v[100:101] offset:4096
	v_cvt_pk_bf16_f32 v66, v66, v67
	v_cvt_pk_bf16_f32 v67, v68, v69
	v_add_u32_e32 v34, v204, v155
	ds_write_b64 v34, v[66:67] offset:2048
	v_mov_b32_e32 v66, v92
	v_mov_b32_e32 v67, v82
	v_mov_b32_e32 v82, v93
	v_mov_b32_e32 v92, v94
	v_mov_b32_e32 v93, v90
	v_mov_b32_e32 v90, v95
	v_pk_mul_f32 v[94:95], v[134:135], v[136:137]
	v_pk_mul_f32 v[102:103], v[132:133], v[130:131]
	v_rcp_f32_e32 v134, v94
	v_rcp_f32_e32 v132, v102
	v_rcp_f32_e32 v133, v103
	v_rcp_f32_e32 v135, v95
	v_pk_mul_f32 v[70:71], v[112:113], v[70:71]
	v_pk_mul_f32 v[72:73], v[114:115], v[72:73]
	v_pk_mul_f32 v[104:105], v[104:105], v[132:133]
	v_pk_mul_f32 v[106:107], v[106:107], v[134:135]
	v_pk_mul_f32 v[110:111], v[110:111], v[134:135]
; #define LAS __attribute__((address_space(3)))
; __device__ __forceinline__ void rw_scan(const bf16* R, const bf16* K, const bf16* V, const bf16* WM, const bf16* A, const float* k_k, const float* k_a, bf16* Y, LAS unsigned char* lds) {
;     ...
;                         o.x = pk2(alb[0], alb[1]); o.y = pk2(alb[2], alb[3]); *(LAS v2u*)(tmp + RWT_AB + s * 128 + 8 * fr) = o;
;                         o.x = pk2(bet[0], bet[1]); o.y = pk2(bet[2], bet[3]); *(LAS v2u*)(tmp + RWT_BT + s * 128 + 8 * fr) = o;
;                         o.x = pk2(ktl[0], ktl[1]); o.y = pk2(ktl[2], ktl[3]); *(LAS v2u*)(tmp + RWT_KT + s * 128 + 8 * fr) = o;
;                         o.x = pk2(rb[0], rb[1]); o.y = pk2(rb[2], rb[3]); *(LAS v2u*)(slot + RWS_RB + s * 128 + 8 * fr) = o;
; #pragma unroll
;                         for (int x = 0; x < 4; ++x) { kgt[x][j] = ktl[x] * all[x]; bgt[x][j] = -(bet[x] * all[x]); abt[x][j] = alb[x]; }
;                     }
; #pragma unroll
;                     for (int x = 0; x < 4; ++x) {
;                         const int kch = 4 * fr + x;
;                         v2u o;
;                         o.x = pk2(kgt[x][0], kgt[x][1]); o.y = pk2(kgt[x][2], kgt[x][3]); *(LAS v2u*)(slot + RWS_KGT + rwz(kch) * 32 + 8 * fq) = o;
;                         o.x = pk2(bgt[x][0], bgt[x][1]); o.y = pk2(bgt[x][2], bgt[x][3]); *(LAS v2u*)(slot + RWS_BGT + rwz(kch) * 32 + 8 * fq) = o;
;                         o.x = pk2(abt[x][0], abt[x][1]); o.y = pk2(abt[x][2], abt[x][3]); *(LAS v2u*)(tmp + RWT_ABT + rwz(kch) * 32 + 8 * fq) = o;
;                     }
;                     if (fq == 0) *(LAS f32x4*)(slot + RWS_G15 + 16 * fr) = all;
;                     const unsigned vlo = (unsigned)cu.v[0] | ((unsigned)cu.v[1] << 16), vhi = (unsigned)cu.v[2] | ((unsigned)cu.v[3] << 16);
;                     { v2u o; o.x = vlo; o.y = vhi; *(LAS v2u*)(slot + RWS_VCI + 8 * lane) = o; }
;                     LDS_WAIT(); asm volatile("" ::: "memory");
;                     f32x4 nac = (f32x4){0.f, 0.f, 0.f, 0.f}, kat = nac, krt = nac, nrt = nac;
; #pragma unroll
;                     for (int p = 0; p < 2; ++p) {
;                         const int kb = (32 * p + 8 * fq) * 2;
;                         const bf16x8 oAB = lds_op16(tmp + RWT_AB, fr, kb), oBT = lds_op16(tmp + RWT_BT, fr, kb), oKT = lds_op16(tmp + RWT_KT, fr, kb), oRB = lds_op16(slot + RWS_RB, fr, kb);
	v_pk_mul_f32 v[108:109], v[108:109], v[132:133]
	v_cvt_pk_bf16_f32 v112, v72, v73
	v_cvt_pk_bf16_f32 v113, v70, v71
	v_add_u32_e32 v34, v147, v156
	v_cvt_pk_bf16_f32 v114, v104, v105
	v_cvt_pk_bf16_f32 v115, v106, v107
	v_pk_mul_f32 v[76:77], v[94:95], v[76:77]
	v_pk_mul_f32 v[74:75], v[102:103], v[74:75]
	ds_write2st64_b64 v34, v[112:113], v[114:115] offset1:4
	v_cvt_pk_bf16_f32 v112, v108, v109
	v_cvt_pk_bf16_f32 v113, v110, v111
	ds_write_b64 v34, v[112:113] offset:4096
	v_cvt_pk_bf16_f32 v74, v74, v75
	v_cvt_pk_bf16_f32 v75, v76, v77
	v_add_u32_e32 v34, v204, v156
	ds_write_b64 v34, v[74:75] offset:2048
	v_pk_mul_f32 v[74:75], v[126:127], v[136:137]
	v_pk_mul_f32 v[76:77], v[128:129], v[130:131]
	v_rcp_f32_e32 v114, v74
	v_rcp_f32_e32 v112, v76
	v_rcp_f32_e32 v113, v77
	v_rcp_f32_e32 v115, v75
	v_lshlrev_b32_e32 v96, 16, v97
	v_and_b32_e32 v97, 0xffff0000, v97
	v_pk_mul_f32 v[94:95], v[122:123], v[94:95]
	v_pk_mul_f32 v[102:103], v[124:125], v[102:103]
	v_pk_mul_f32 v[74:75], v[74:75], v[96:97]
	v_pk_mul_f32 v[96:97], v[116:117], v[114:115]
	v_pk_mul_f32 v[84:85], v[84:85], v[112:113]
	v_pk_mul_f32 v[76:77], v[76:77], v[98:99]
	v_pk_mul_f32 v[98:99], v[120:121], v[114:115]
	v_pk_mul_f32 v[112:113], v[118:119], v[112:113]
	v_cvt_pk_bf16_f32 v114, v102, v103
	v_cvt_pk_bf16_f32 v115, v94, v95
	v_add_u32_e32 v34, v147, v157
	v_cvt_pk_bf16_f32 v116, v84, v85
	v_cvt_pk_bf16_f32 v117, v96, v97
	ds_write2st64_b64 v34, v[114:115], v[116:117] offset1:4
	v_cvt_pk_bf16_f32 v114, v112, v113
	v_cvt_pk_bf16_f32 v115, v98, v99
	ds_write_b64 v34, v[114:115] offset:4096
	v_cvt_pk_bf16_f32 v76, v76, v77
	v_cvt_pk_bf16_f32 v77, v74, v75
	v_add_u32_e32 v34, v204, v157
	v_mov_b32_e32 v68, v168
	v_mov_b32_e32 v69, v78
	ds_write_b64 v34, v[76:77] offset:2048
	v_mov_b32_e32 v74, v108
	v_mov_b32_e32 v75, v112
	v_mov_b32_e32 v76, v104
	v_mov_b32_e32 v77, v84
	v_pk_mul_f32 v[66:67], v[8:9], v[66:67] op_sel_hi:[0,1]
	v_pk_mul_f32 v[68:69], v[68:69], v[8:9] op_sel_hi:[1,0] neg_lo:[0,1] neg_hi:[0,1]
	v_pk_mul_f32 v[74:75], v[8:9], v[74:75] op_sel_hi:[0,1]
	v_pk_mul_f32 v[76:77], v[76:77], v[8:9] op_sel_hi:[1,0] neg_lo:[0,1] neg_hi:[0,1]
	v_add_u32_e32 v34, s74, v139
	v_mov_b32_e32 v78, v169
	v_mov_b32_e32 v112, v109
	v_mov_b32_e32 v84, v105
	v_cvt_pk_bf16_f32 v66, v66, v67
	v_cvt_pk_bf16_f32 v67, v74, v75
	v_add_u32_e32 v74, v34, v158
	v_cvt_pk_bf16_f32 v68, v68, v69
	v_cvt_pk_bf16_f32 v69, v76, v77
	v_pk_mul_f32 v[82:83], v[8:9], v[82:83] op_sel:[1,0]
	v_pk_mul_f32 v[78:79], v[78:79], v[8:9] op_sel:[0,1] neg_lo:[0,1] neg_hi:[0,1]
	v_pk_mul_f32 v[108:109], v[8:9], v[112:113] op_sel:[1,0]
	v_pk_mul_f32 v[84:85], v[84:85], v[8:9] op_sel:[0,1] neg_lo:[0,1] neg_hi:[0,1]
	ds_write2st64_b64 v74, v[66:67], v[68:69] offset0:8 offset1:12
	v_cvt_pk_bf16_f32 v66, v64, v88
	v_cvt_pk_bf16_f32 v67, v72, v102
	v_add_u32_e32 v64, v148, v158
	v_mov_b32_e32 v100, v170
	v_mov_b32_e32 v101, v80
	v_mov_b32_e32 v104, v110
	v_mov_b32_e32 v105, v98
	v_mov_b32_e32 v112, v106
	v_mov_b32_e32 v113, v96
	ds_write_b64 v64, v[66:67] offset:6144
	v_cvt_pk_bf16_f32 v66, v82, v83
	v_cvt_pk_bf16_f32 v67, v108, v109
	v_add_u32_e32 v64, v34, v159
	v_cvt_pk_bf16_f32 v68, v78, v79
	v_cvt_pk_bf16_f32 v69, v84, v85
	v_pk_mul_f32 v[92:93], v[10:11], v[92:93] op_sel_hi:[0,1]
	v_pk_mul_f32 v[100:101], v[100:101], v[10:11] op_sel_hi:[1,0] neg_lo:[0,1] neg_hi:[0,1]
	v_pk_mul_f32 v[104:105], v[10:11], v[104:105] op_sel_hi:[0,1]
	v_pk_mul_f32 v[112:113], v[112:113], v[10:11] op_sel_hi:[1,0] neg_lo:[0,1] neg_hi:[0,1]
	ds_write2st64_b64 v64, v[66:67], v[68:69] offset0:8 offset1:12
	v_cvt_pk_bf16_f32 v64, v65, v89
	v_cvt_pk_bf16_f32 v65, v73, v103
	v_add_u32_e32 v66, v148, v159
	v_mov_b32_e32 v80, v171
	v_mov_b32_e32 v98, v111
	v_mov_b32_e32 v96, v107
	ds_write_b64 v66, v[64:65] offset:6144
	v_cvt_pk_bf16_f32 v64, v92, v93
	v_cvt_pk_bf16_f32 v65, v104, v105
	v_add_u32_e32 v68, v34, v160
	v_cvt_pk_bf16_f32 v66, v100, v101
	v_cvt_pk_bf16_f32 v67, v112, v113
	v_pk_mul_f32 v[90:91], v[10:11], v[90:91] op_sel:[1,0]
	v_pk_mul_f32 v[80:81], v[80:81], v[10:11] op_sel:[0,1] neg_lo:[0,1] neg_hi:[0,1]
	v_pk_mul_f32 v[98:99], v[10:11], v[98:99] op_sel:[1,0]
	v_pk_mul_f32 v[96:97], v[96:97], v[10:11] op_sel:[0,1] neg_lo:[0,1] neg_hi:[0,1]
	ds_write2st64_b64 v68, v[64:65], v[66:67] offset0:8 offset1:12
	v_cvt_pk_bf16_f32 v64, v32, v86
	v_cvt_pk_bf16_f32 v65, v70, v94
	v_add_u32_e32 v32, v148, v160
	ds_write_b64 v32, v[64:65] offset:6144
	v_cvt_pk_bf16_f32 v64, v90, v91
	v_cvt_pk_bf16_f32 v65, v98, v99
	v_add_u32_e32 v32, v34, v161
	v_cvt_pk_bf16_f32 v66, v80, v81
	v_cvt_pk_bf16_f32 v67, v96, v97
	ds_write2st64_b64 v32, v[64:65], v[66:67] offset0:8 offset1:12
	v_cvt_pk_bf16_f32 v32, v33, v87
	v_cvt_pk_bf16_f32 v33, v71, v95
	v_add_u32_e32 v34, v148, v161
	ds_write_b64 v34, v[32:33] offset:6144
	s_and_saveexec_b64 s[68:69], s[42:43]
	v_add_u32_e32 v32, s74, v149
	ds_write_b128 v32, v[8:11] offset:8192
	s_or_b64 exec, exec, s[68:69]
	v_lshlrev_b32_e32 v8, 16, v201
	v_lshlrev_b32_e32 v9, 16, v35
	v_or_b32_sdwa v8, v8, v200 dst_sel:DWORD dst_unused:UNUSED_PAD src0_sel:DWORD src1_sel:WORD_0
	v_or_b32_sdwa v9, v9, v199 dst_sel:DWORD dst_unused:UNUSED_PAD src0_sel:DWORD src1_sel:WORD_0
	v_add_u32_e32 v10, s74, v140
	ds_write_b64 v10, v[8:9] offset:10496
	ds_read_b128 v[32:35], v194 offset:2048
	ds_read_b128 v[64:67], v194
	ds_read_b128 v[68:71], v194 offset:64
	ds_read_b128 v[72:75], v194 offset:2112
	ds_read_b128 v[80:83], v194 offset:4096
	ds_read_b128 v[84:87], v194 offset:4160
	v_add3_u32 v10, s74, v138, v141
	ds_read_b128 v[88:91], v10 offset:2048
	ds_read_b128 v[92:95], v10 offset:2112
	s_waitcnt lgkmcnt(6)
; #define LAS __attribute__((address_space(3)))
; #define LDS_WAIT() asm volatile("s_waitcnt lgkmcnt(0)" ::: "memory")
; __device__ __forceinline__ unsigned pk2(float lo, float hi) { const f32x2_t v = {lo, hi}; const bf16x2_t b = __builtin_convertvector(v, bf16x2_t); return __builtin_bit_cast(unsigned, b); }
; __device__ __forceinline__ void rw_scan(const bf16* R, const bf16* K, const bf16* V, const bf16* WM, const bf16* A, const float* k_k, const float* k_a, bf16* Y, LAS unsigned char* lds) {
;     ...
;                     for (int p = 0; p < 2; ++p) {
;                         const int kb = (32 * p + 8 * fq) * 2;
;                         const bf16x8 oAB = lds_op16(tmp + RWT_AB, fr, kb), oBT = lds_op16(tmp + RWT_BT, fr, kb), oKT = lds_op16(tmp + RWT_KT, fr, kb), oRB = lds_op16(slot + RWS_RB, fr, kb);
;                         nac = __builtin_amdgcn_mfma_f32_16x16x32_bf16(oBT, oAB, nac, 0, 0, 0);
;                         kat = __builtin_amdgcn_mfma_f32_16x16x32_bf16(oKT, oAB, kat, 0, 0, 0);
;                         krt = __builtin_amdgcn_mfma_f32_16x16x32_bf16(oKT, oRB, krt, 0, 0, 0);
;                         nrt = __builtin_amdgcn_mfma_f32_16x16x32_bf16(oBT, oRB, nrt, 0, 0, 0);
;                     }
; #pragma unroll
;                     for (int i = 0; i < 4; ++i) { const int rr_ = 4 * fq + i;
;                         if (rr_ >= fr) { nac[i] = 0.f; kat[i] = 0.f; }
;                         if (rr_ > fr) { krt[i] = 0.f; nrt[i] = 0.f; } }
;                     { u32x4_t o; o.x = pk2(krt[0], krt[1]); o.y = pk2(krt[2], krt[3]); o.z = pk2(-nrt[0], -nrt[1]); o.w = pk2(-nrt[2], -nrt[3]); *(LAS u32x4_t*)(slot + RWS_KNI + 16 * lane) = o; }
;                     LDS_WAIT(); asm volatile("" ::: "memory");
;                     *(LAS f32x4*)(tmp + RWT_NM + (fr * 16 + 4 * fq) * 4) = nac;
;                     LDS_WAIT(); asm volatile("" ::: "memory");
;                     float Tc[16];
;                     f32x4 nvv[16][4];
;     ...
;                     RW_LD_ROWS(1, 8) RW_LD_ROWS(9, 12)
;                     asm volatile("" ::: "memory");
;                     RW_DO_ROWS(0, 8)
;                     RW_LD_ROWS(13, 15)
;                     asm volatile("" ::: "memory");
;                     RW_DO_ROWS(9, 12)
;                     RW_DO_ROWS(13, 15)
	v_mfma_f32_16x16x32_bf16 v[76:79], v[32:35], v[64:67], 0
	v_mov_b32_e32 v10, s93
	v_add_u32_e32 v199, s74, v27
	s_or_b64 vcc, s[64:65], s[48:49]
	s_waitcnt lgkmcnt(1)
	v_mfma_f32_16x16x32_bf16 v[32:35], v[32:35], v[88:91], 0
	v_mov_b32_e32 v237, v236
	v_mfma_f32_16x16x32_bf16 v[64:67], v[80:83], v[64:67], 0
	v_mfma_f32_16x16x32_bf16 v[80:83], v[80:83], v[88:91], 0
	s_waitcnt lgkmcnt(0)
	v_mfma_f32_16x16x32_bf16 v[32:35], v[72:75], v[92:95], v[32:35]
	v_mfma_f32_16x16x32_bf16 v[76:79], v[72:75], v[68:71], v[76:79]
	v_mov_b32_e32 v72, s93
	s_nop 5
	v_cndmask_b32_e64 v11, v32, v72, s[50:51]
	v_mfma_f32_16x16x32_bf16 v[72:75], v[84:87], v[92:95], v[80:83]
	v_mfma_f32_16x16x32_bf16 v[64:67], v[84:87], v[68:71], v[64:67]
	v_cndmask_b32_e64 v71, 0, v79, s[54:55]
	s_nop 5
	v_cndmask_b32_e64 v10, v72, v10, s[50:51]
	v_cndmask_b32_e64 v10, v10, v72, s[48:49]
	v_cndmask_b32_e64 v72, 0, v73, s[48:49]
	v_cvt_pk_bf16_f32 v72, v10, v72
	v_cndmask_b32_e64 v10, v11, v32, s[48:49]
	v_cndmask_b32_e64 v11, 0, v33, s[48:49]
	v_cndmask_b32_e64 v73, v74, 0, s[52:53]
	v_cndmask_b32_e64 v74, v75, 0, s[56:57]
	v_xor_b32_e32 v10, 0x80000000, v10
	v_xor_b32_e32 v11, 0x80000000, v11
	v_cvt_pk_bf16_f32 v73, v73, v74
	v_cvt_pk_bf16_f32 v74, v10, v11
	v_cndmask_b32_e64 v10, v34, 0, s[52:53]
	v_xor_b32_e32 v10, 0x80000000, v10
	v_cndmask_b32_e64 v11, -v35, v251, s[56:57]
	v_cvt_pk_bf16_f32 v75, v10, v11
	ds_write_b128 v199, v[72:75] offset:8448
	v_cndmask_b32_e64 v70, 0, v78, s[62:63]
	v_cndmask_b32_e64 v69, 0, v77, s[64:65]
	v_cndmask_b32_e32 v68, 0, v76, vcc
	ds_write_b128 v195, v[68:71]
	v_mov_b32_e32 v10, s90
	ds_read_b128 v[32:35], v10 offset:64
	ds_read_b128 v[68:71], v10 offset:128
	s_waitcnt lgkmcnt(0)
	ds_read_b128 v[70:73], v10 offset:192
	ds_read_b128 v[74:77], v10 offset:256
	ds_read_b128 v[78:81], v10 offset:320
	ds_read_b128 v[82:85], v10 offset:336
	s_waitcnt lgkmcnt(0)
	ds_read_b128 v[84:87], v10 offset:384
	ds_read_b128 v[88:91], v10 offset:400
	s_waitcnt lgkmcnt(0)
	ds_read_b128 v[90:93], v10 offset:448
	ds_read_b128 v[94:97], v10 offset:464
	ds_read_b128 v[98:101], v10 offset:512
	ds_read_b128 v[102:105], v10 offset:528
	ds_read_b128 v[106:109], v10 offset:576
	ds_read_b128 v[110:113], v10 offset:592
	ds_read_b128 v[114:117], v10 offset:608
	v_fma_f32 v11, -v162, v32, v163
	v_fma_f32 v32, -v162, v68, v180
	s_waitcnt lgkmcnt(0)
	ds_read_b128 v[116:119], v10 offset:640
	ds_read_b128 v[120:123], v10 offset:656
	ds_read_b128 v[124:127], v10 offset:672
	v_fma_f32 v115, -v69, v11, v32
	v_fma_f32 v32, -v162, v70, v181
	s_waitcnt lgkmcnt(0)
	ds_read_b128 v[126:129], v10 offset:704
	ds_read_b128 v[130:133], v10 offset:720
	ds_read_b128 v[134:137], v10 offset:736
	ds_read_b128 v[164:167], v10 offset:768
	ds_read_b128 v[168:171], v10 offset:784
	ds_read_b128 v[172:175], v10 offset:800
	v_fma_f32 v32, -v71, v11, v32
	s_waitcnt lgkmcnt(3)
	v_fma_f32 v137, -v72, v115, v32
	v_fma_f32 v32, -v162, v74, v182
	v_fma_f32 v32, -v11, v75, v32
	v_fma_f32 v32, -v76, v115, v32
	v_fma_f32 v200, -v77, v137, v32
	v_fma_f32 v32, -v162, v78, v183
	v_fma_f32 v32, -v11, v79, v32
	v_fma_f32 v32, -v80, v115, v32
	v_fma_f32 v32, -v81, v137, v32
	v_fma_f32 v201, -v82, v200, v32
	v_fma_f32 v32, -v162, v84, v184
	v_fma_f32 v32, -v11, v85, v32
	v_fma_f32 v32, -v115, v86, v32
	v_fma_f32 v32, -v87, v137, v32
	v_fma_f32 v32, -v88, v200, v32
	v_fma_f32 v202, -v89, v201, v32
	v_fma_f32 v32, -v162, v90, v185
	v_fma_f32 v32, -v11, v91, v32
	v_fma_f32 v32, -v115, v92, v32
	v_fma_f32 v32, -v137, v93, v32
	v_fma_f32 v32, -v200, v94, v32
	v_fma_f32 v32, -v95, v201, v32
	v_fma_f32 v203, -v96, v202, v32
	v_fma_f32 v32, -v162, v98, v186
	v_fma_f32 v32, -v11, v99, v32
	v_fma_f32 v32, -v115, v100, v32
	v_fma_f32 v32, -v137, v101, v32
	v_fma_f32 v32, -v200, v102, v32
	v_fma_f32 v32, -v201, v103, v32
	v_fma_f32 v32, -v104, v202, v32
	v_fma_f32 v104, -v105, v203, v32
	ds_read_b128 v[32:35], v10 offset:832
	ds_read_b128 v[68:71], v10 offset:848
	ds_read_b128 v[72:75], v10 offset:864
	ds_read_b128 v[76:79], v10 offset:880
	s_waitcnt lgkmcnt(0)
	ds_read_b128 v[78:81], v10 offset:896
	ds_read_b128 v[82:85], v10 offset:912
	ds_read_b128 v[86:89], v10 offset:928
	ds_read_b128 v[90:93], v10 offset:944
	s_waitcnt lgkmcnt(0)
	ds_read_b128 v[92:95], v10 offset:960
	ds_read_b128 v[96:99], v10 offset:976
	ds_read_b128 v[100:103], v10 offset:992
	ds_read_b128 v[176:179], v10 offset:1008
	v_fma_f32 v10, -v162, v106, v187
	v_fma_f32 v77, -v162, v116, v188
	v_fma_f32 v105, -v162, v126, v189
	v_fma_f32 v106, -v162, v164, v190
	v_fma_f32 v32, -v162, v32, v191
	v_fma_f32 v10, -v11, v107, v10
	v_fma_f32 v77, -v11, v117, v77
	v_fma_f32 v105, -v11, v127, v105
	v_fma_f32 v106, -v11, v165, v106
	v_fma_f32 v32, -v11, v33, v32
	v_fma_f32 v10, -v115, v108, v10
	v_fma_f32 v77, -v115, v118, v77
	v_fma_f32 v105, -v115, v128, v105
	v_fma_f32 v106, -v115, v166, v106
	v_fma_f32 v32, -v115, v34, v32
	v_fma_f32 v10, -v137, v109, v10
	v_fma_f32 v77, -v137, v119, v77
	v_fma_f32 v105, -v137, v129, v105
	v_fma_f32 v106, -v137, v167, v106
	v_fma_f32 v32, -v137, v35, v32
	v_fma_f32 v33, -v162, v78, v192
	s_waitcnt lgkmcnt(3)
; #define LAS __attribute__((address_space(3)))
; __device__ __forceinline__ void rw_scan(const bf16* R, const bf16* K, const bf16* V, const bf16* WM, const bf16* A, const float* k_k, const float* k_a, bf16* Y, LAS unsigned char* lds) {
;     ...
;                     RW_DO_ROWS(0, 8)
;                     RW_LD_ROWS(13, 15)
;                     asm volatile("" ::: "memory");
;                     RW_DO_ROWS(9, 12)
;                     RW_DO_ROWS(13, 15)
;     ...
; #pragma unroll
;                     for (int e = 0; e < 4; ++e) {
;                         float tv = Tc[0];
; #pragma unroll
;                         for (int s = 0; s < 16; ++s) if (s == 4 * fq + e) tv = Tc[s];
;                         *(LAS unsigned short*)(tmp + RWT_TM + ((4 * fq + e) * 16 + fr) * 2) = (unsigned short)f2bf(tv);
;                     }
;                     LDS_WAIT(); asm volatile("" ::: "memory");
;                     const v2u tq = lds_8(tmp + RWT_TM + (fr * 16 + 4 * fq) * 2);
;                     const bf16x8 opT = mk8(tq.x, tq.y, 0u, 0u);
;                     f32x4 xac = __builtin_amdgcn_mfma_f32_16x16x32_bf16(mk8(pk2(kat[0], kat[1]), pk2(kat[2], kat[3]), 0u, 0u), mk8(vlo, vhi, 0u, 0u), (f32x4){0.f, 0.f, 0.f, 0.f}, 0, 0, 0);
;                     const f32x4 wvv = __builtin_amdgcn_mfma_f32_16x16x32_bf16(opT, mk8(pk2(xac[0], xac[1]), pk2(xac[2], xac[3]), 0u, 0u), (f32x4){0.f, 0.f, 0.f, 0.f}, 0, 0, 0);
;                     *(LAS f32x4*)(slot + RWS_WVI + 16 * lane) = wvv;
;                     f32x4 aht[4];
; #pragma unroll
;                     for (int nt = 0; nt < 4; ++nt) {
;                         const v2u ab = lds_8(tmp + RWT_ABT + rwz(16 * nt + fr) * 32 + 8 * fq);
;                         aht[nt] = __builtin_amdgcn_mfma_f32_16x16x32_bf16(mk8(ab.x, ab.y, 0u, 0u), opT, (f32x4){0.f, 0.f, 0.f, 0.f}, 0, 0, 0);
;                     }
; #pragma unroll
;                     for (int p = 0; p < 2; ++p) { u32x4_t o; o.x = pk2(aht[2 * p][0], aht[2 * p][1]); o.y = pk2(aht[2 * p][2], aht[2 * p][3]); o.z = pk2(aht[2 * p + 1][0], aht[2 * p + 1][1]); o.w = pk2(aht[2 * p + 1][2], aht[2 * p + 1][3]);
;                         *(LAS u32x4_t*)(slot + RWS_AH + (p * 64 + lane) * 16) = o; }
;                     LDS_WAIT(); asm volatile("" ::: "memory");
;                     if (lane == 0) flg[cj % RW_NSLOT] = (unsigned)(cj + 1);
	v_fma_f32 v34, -v162, v92, v193
	v_fma_f32 v10, -v200, v110, v10
	v_fma_f32 v77, -v200, v120, v77
	v_fma_f32 v105, -v200, v130, v105
	v_fma_f32 v106, -v200, v168, v106
	v_fma_f32 v32, -v200, v68, v32
	v_fma_f32 v33, -v11, v79, v33
	v_fma_f32 v34, -v11, v93, v34
	v_fma_f32 v10, -v201, v111, v10
	v_fma_f32 v77, -v201, v121, v77
	v_fma_f32 v105, -v201, v131, v105
	v_fma_f32 v106, -v201, v169, v106
	v_fma_f32 v32, -v201, v69, v32
	v_fma_f32 v33, -v115, v80, v33
	v_fma_f32 v34, -v115, v94, v34
	v_fma_f32 v10, -v112, v202, v10
	v_fma_f32 v77, -v202, v122, v77
	v_fma_f32 v105, -v202, v132, v105
	v_fma_f32 v106, -v202, v170, v106
	v_fma_f32 v32, -v202, v70, v32
	v_fma_f32 v33, -v137, v81, v33
	v_fma_f32 v34, -v137, v95, v34
	v_fma_f32 v10, -v113, v203, v10
	v_fma_f32 v77, -v123, v203, v77
	v_fma_f32 v105, -v203, v133, v105
	v_fma_f32 v106, -v203, v171, v106
	v_fma_f32 v32, -v203, v71, v32
	v_fma_f32 v33, -v200, v82, v33
	s_waitcnt lgkmcnt(2)
	v_fma_f32 v34, -v200, v96, v34
	v_fma_f32 v10, -v114, v104, v10
	v_fma_f32 v77, -v124, v104, v77
	v_fma_f32 v105, -v104, v134, v105
	v_fma_f32 v106, -v104, v172, v106
	v_fma_f32 v32, -v104, v72, v32
	v_fma_f32 v33, -v201, v83, v33
	v_fma_f32 v34, -v201, v97, v34
	v_fma_f32 v77, -v125, v10, v77
	v_fma_f32 v105, -v135, v10, v105
	v_fma_f32 v106, -v10, v173, v106
	v_fma_f32 v32, -v10, v73, v32
	v_fma_f32 v33, -v202, v84, v33
	v_fma_f32 v34, -v202, v98, v34
	v_fma_f32 v105, -v136, v77, v105
	v_fma_f32 v106, -v174, v77, v106
	v_fma_f32 v32, -v77, v74, v32
	v_fma_f32 v33, -v203, v85, v33
	v_fma_f32 v34, -v203, v99, v34
	v_cndmask_b32_e64 v11, v162, v11, s[42:43]
	v_fma_f32 v106, -v175, v105, v106
	v_fma_f32 v32, -v75, v105, v32
	v_fma_f32 v33, -v104, v86, v33
	s_waitcnt lgkmcnt(1)
	v_fma_f32 v34, -v104, v100, v34
	v_cndmask_b32_e64 v11, v11, v201, s[58:59]
	v_fma_f32 v32, -v76, v106, v32
	v_fma_f32 v33, -v10, v87, v33
	v_fma_f32 v34, -v10, v101, v34
	v_cndmask_b32_e64 v10, v11, v10, s[60:61]
	v_cndmask_b32_e64 v10, v10, v32, s[46:47]
	v_fma_f32 v33, -v77, v88, v33
	v_cvt_pk_bf16_f32 v10, v10, s0
	v_fma_f32 v33, -v105, v89, v33
	ds_write_b16 v196, v10 offset:2080
	v_cndmask_b32_e64 v10, v162, v115, s[42:43]
	v_fma_f32 v33, -v90, v106, v33
	v_cndmask_b32_e64 v10, v10, v202, s[58:59]
	v_fma_f32 v33, -v91, v32, v33
	v_cndmask_b32_e64 v10, v10, v77, s[60:61]
	v_fma_f32 v34, -v77, v102, v34
	v_cndmask_b32_e64 v10, v10, v33, s[46:47]
	v_fma_f32 v34, -v105, v103, v34
	v_cvt_pk_bf16_f32 v10, v10, s0
	s_waitcnt lgkmcnt(1)
	v_fma_f32 v34, -v106, v176, v34
	ds_write_b16 v196, v10 offset:2112
	v_cndmask_b32_e64 v10, v162, v137, s[42:43]
	v_fma_f32 v34, -v177, v32, v34
	v_cndmask_b32_e64 v35, v162, v200, s[58:59]
	v_cndmask_b32_e64 v10, v10, v203, s[58:59]
	v_fma_f32 v34, -v178, v33, v34
	v_cndmask_b32_e64 v35, v35, v104, s[60:61]
	v_cndmask_b32_e64 v10, v10, v105, s[60:61]
	v_cndmask_b32_e64 v35, v35, v106, s[46:47]
	v_cndmask_b32_e64 v10, v10, v34, s[46:47]
	v_cvt_pk_bf16_f32 v35, v35, s0
	v_cvt_pk_bf16_f32 v10, v10, s0
	ds_write_b16 v196, v35 offset:2048
	ds_write_b16 v196, v10 offset:2144
	v_cndmask_b32_e64 v10, 0, v67, s[54:55]
	v_cndmask_b32_e64 v11, 0, v66, s[62:63]
	v_cndmask_b32_e64 v32, 0, v65, s[64:65]
	v_cndmask_b32_e32 v33, 0, v64, vcc
	v_cvt_pk_bf16_f32 v32, v33, v32
	v_cvt_pk_bf16_f32 v33, v11, v10
	v_mov_b32_e32 v34, v236
	v_mov_b32_e32 v35, v236
	ds_read_b64 v[234:235], v197 offset:2048
	v_mov_b32_e32 v10, v236
	v_mov_b32_e32 v11, v236
	v_mov_b32_e32 v66, v236
	v_mov_b32_e32 v67, v236
	v_mfma_f32_16x16x32_bf16 v[8:11], v[32:35], v[8:11], 0
	v_add_u32_e32 v32, v148, v151
	v_add_u32_e32 v34, v148, v152
	v_add_u32_e32 v35, v148, v153
	v_mov_b32_e32 v70, v236
	v_mov_b32_e32 v71, v236
	s_nop 2
	v_cvt_pk_bf16_f32 v8, v8, v9
	v_cvt_pk_bf16_f32 v9, v10, v11
	v_mov_b32_e32 v10, v236
	v_mov_b32_e32 v11, v236
	s_waitcnt lgkmcnt(0)
	s_nop 0
	v_mfma_f32_16x16x32_bf16 v[8:11], v[234:237], v[8:11], 0
	s_nop 7
	ds_write_b128 v199, v[8:11] offset:9472
	v_add_u32_e32 v8, v148, v150
	ds_read_b64 v[8:9], v8 offset:6144
	v_mov_b32_e32 v10, v236
	v_mov_b32_e32 v11, v236
	ds_read_b64 v[32:33], v32 offset:6144
	ds_read_b64 v[64:65], v34 offset:6144
	ds_read_b64 v[68:69], v35 offset:6144
	v_mov_b32_e32 v34, v236
	v_mov_b32_e32 v35, v236
	s_waitcnt lgkmcnt(3)
	v_mfma_f32_16x16x32_bf16 v[8:11], v[8:11], v[234:237], 0
	s_waitcnt lgkmcnt(2)
	v_mfma_f32_16x16x32_bf16 v[32:35], v[32:35], v[234:237], 0
	s_nop 5
	v_cvt_pk_bf16_f32 v8, v8, v9
	v_cvt_pk_bf16_f32 v9, v10, v11
	s_waitcnt lgkmcnt(1)
	v_mfma_f32_16x16x32_bf16 v[64:67], v[64:67], v[234:237], 0
	s_waitcnt lgkmcnt(0)
	v_mfma_f32_16x16x32_bf16 v[68:71], v[68:71], v[234:237], 0
	v_cvt_pk_bf16_f32 v10, v32, v33
	v_cvt_pk_bf16_f32 v11, v34, v35
	ds_write_b128 v199, v[8:11]
	s_nop 2
	v_cvt_pk_bf16_f32 v8, v64, v65
	v_cvt_pk_bf16_f32 v9, v66, v67
	v_cvt_pk_bf16_f32 v10, v68, v69
	v_cvt_pk_bf16_f32 v11, v70, v71
	ds_write_b128 v199, v[8:11] offset:1024
	s_waitcnt lgkmcnt(0)
	s_and_saveexec_b64 s[68:69], s[40:41]
	s_cbranch_execz .LBB0_495
	s_lshl_b32 s75, s92, 2
	s_add_i32 s75, s75, 0
	s_add_i32 s74, s89, 1
	s_add_i32 s75, s75, 0x26c00
	v_mov_b32_e32 v8, s75
	v_mov_b32_e32 v9, s74
	ds_write_b32 v8, v9
	s_branch .LBB0_495

;     __device__ __forceinline__ void operator()(const f32x4 (&acc)[2][2][4][2], const Unit& u, int wr, int wc, int fr, int fq) const {
;         const int row0 = u.pm * BM + wr * 64 + fr; int colt = u.pn * BM; bf16_t* base = O; int t = 0;
;         if (split_cols) { t = colt / split_cols; base += (size_t)t * split_stride; colt -= t * split_cols; }
;         const float sc = (MODE == 0 && t == 0) ? scale0 : 1.f;
;         const int col0 = colt + wc * 32 + 8 * fq;
;         f32x4 lbk[2][2];
; #pragma unroll
;         for (int bj = 0; bj < 2; ++bj)
; #pragma unroll
;             for (int n = 0; n < 2; ++n) lbk[bj][n] = (MODE == 2 && t == 1) ? *(const f32x4*)(aux + col0 + bj * HALF + 4 * n) : (f32x4){0.f, 0.f, 0.f, 0.f};
;         float rsv[2][4];
;         if (rs) {
;             f32x4 part[2][4];
; #pragma unroll
;             for (int ai = 0; ai < 2; ++ai)
; #pragma unroll
;                 for (int m = 0; m < 4; ++m) part[ai][m] = *(const f32x4*)(rs + (size_t)(row0 + ai * HALF + m * 16) * 16 + 4 * fq);
; #pragma unroll
;             for (int ai = 0; ai < 2; ++ai)
; #pragma unroll
;                 for (int m = 0; m < 4; ++m) { float s = (part[ai][m][0] + part[ai][m][1]) + (part[ai][m][2] + part[ai][m][3]); s += __shfl_xor(s, 16); s += __shfl_xor(s, 32);
;                     rsv[ai][m] = sc / sqrtf(s * (1.0f / 1024.0f) + 1e-6f); }
.LBB0_2157:
	v_lshl_add_u32 v204, s1, 8, v35
	v_ashrrev_i32_e32 v205, 31, v204
	v_lshlrev_b64 v[132:133], 6, v[204:205]
	v_lshl_add_u64 v[132:133], v[186:187], 0, v[132:133]
	global_load_dwordx4 v[160:163], v[132:133], off
	v_or_b32_e32 v206, 16, v204
	v_ashrrev_i32_e32 v207, 31, v206
	v_lshlrev_b64 v[132:133], 6, v[206:207]
	v_lshl_add_u64 v[132:133], v[186:187], 0, v[132:133]
	global_load_dwordx4 v[156:159], v[132:133], off
	s_ashr_i32 s4, s40, 31
	s_lshr_b32 s4, s4, 30
	s_add_i32 s4, s40, s4
	s_ashr_i32 s6, s4, 2
	s_ashr_i32 s7, s6, 31
	s_lshl_b32 s1, s40, 8
	s_lshl_b64 s[4:5], s[6:7], 26
	s_add_u32 s4, s19, s4
	s_addc_u32 s5, s54, s5
	s_lshl_b32 s6, s6, 10
	s_sub_i32 s1, s1, s6
	s_add_i32 s6, s40, 3
	s_cmp_lt_u32 s6, 7
	v_readlane_b32 s8, v254, 29
	s_cselect_b64 s[6:7], -1, 0
	v_readlane_b32 s9, v254, 30
	s_and_b64 vcc, s[8:9], s[6:7]
	v_mov_b32_e32 v34, 0x3e38aa3b
	v_cndmask_b32_e32 v211, 1.0, v34, vcc
	v_xor_b32_e32 v34, 16, v231
	v_add_u32_e32 v164, 64, v232
	v_cmp_lt_i32_e32 vcc, v34, v164
	v_or_b32_e32 v202, 32, v204
	v_ashrrev_i32_e32 v203, 31, v202
	v_cndmask_b32_e32 v34, v231, v34, vcc
	v_lshlrev_b32_e32 v212, 2, v34
	v_xor_b32_e32 v34, 32, v231
	v_cmp_lt_i32_e32 vcc, v34, v164
	v_lshlrev_b64 v[132:133], 6, v[202:203]
	v_lshl_add_u64 v[132:133], v[186:187], 0, v[132:133]
	v_cndmask_b32_e32 v34, v231, v34, vcc
	v_lshlrev_b32_e32 v213, 2, v34
	global_load_dwordx4 v[152:155], v[132:133], off
	v_or_b32_e32 v200, 48, v204
	v_ashrrev_i32_e32 v201, 31, v200
	v_lshlrev_b64 v[132:133], 6, v[200:201]
	v_lshl_add_u64 v[132:133], v[186:187], 0, v[132:133]
	global_load_dwordx4 v[148:151], v[132:133], off
	v_add_u32_e32 v198, 0x80, v204
	v_ashrrev_i32_e32 v199, 31, v198
	v_lshlrev_b64 v[132:133], 6, v[198:199]
	v_lshl_add_u64 v[132:133], v[186:187], 0, v[132:133]
	global_load_dwordx4 v[144:147], v[132:133], off
	v_add_u32_e32 v196, 0x90, v204
	v_ashrrev_i32_e32 v197, 31, v196
	v_lshlrev_b64 v[132:133], 6, v[196:197]
	v_lshl_add_u64 v[132:133], v[186:187], 0, v[132:133]
	global_load_dwordx4 v[140:143], v[132:133], off
	v_add_u32_e32 v194, 0xa0, v204
	v_ashrrev_i32_e32 v195, 31, v194
	v_lshlrev_b64 v[132:133], 6, v[194:195]
	v_lshl_add_u64 v[132:133], v[186:187], 0, v[132:133]
	global_load_dwordx4 v[136:139], v[132:133], off
	v_add_u32_e32 v192, 0xb0, v204
	v_ashrrev_i32_e32 v193, 31, v192
	v_lshlrev_b64 v[132:133], 6, v[192:193]
	v_lshl_add_u64 v[132:133], v[186:187], 0, v[132:133]
	global_load_dwordx4 v[132:135], v[132:133], off
	s_waitcnt vmcnt(0)
	v_add_f32_e32 v160, v160, v161
	v_add_f32_e32 v162, v162, v163
	v_add_f32_e32 v163, v160, v162
	v_add_f32_e32 v156, v156, v157
	v_add_f32_e32 v158, v158, v159
	v_add_f32_e32 v159, v156, v158
	v_add_f32_e32 v152, v152, v153
	v_add_f32_e32 v154, v154, v155
	v_add_f32_e32 v155, v152, v154
	v_add_f32_e32 v148, v148, v149
	v_add_f32_e32 v150, v150, v151
	v_add_f32_e32 v151, v148, v150
	v_add_f32_e32 v144, v144, v145
	v_add_f32_e32 v146, v146, v147
	v_add_f32_e32 v147, v144, v146
	v_add_f32_e32 v140, v140, v141
	v_add_f32_e32 v142, v142, v143
	v_add_f32_e32 v143, v140, v142
	v_add_f32_e32 v136, v136, v137
	v_add_f32_e32 v138, v138, v139
	v_add_f32_e32 v139, v136, v138
	v_add_f32_e32 v132, v132, v133
	v_add_f32_e32 v134, v134, v135
	v_add_f32_e32 v135, v132, v134
	ds_bpermute_b32 v160, v212, v163
	ds_bpermute_b32 v156, v212, v159
	ds_bpermute_b32 v152, v212, v155
	ds_bpermute_b32 v148, v212, v151
	ds_bpermute_b32 v144, v212, v147
	ds_bpermute_b32 v140, v212, v143
	ds_bpermute_b32 v136, v212, v139
	ds_bpermute_b32 v132, v212, v135
	s_waitcnt lgkmcnt(0)
	v_add_f32_e32 v163, v163, v160
	v_add_f32_e32 v159, v159, v156
	v_add_f32_e32 v155, v155, v152
	v_add_f32_e32 v151, v151, v148
	v_add_f32_e32 v147, v147, v144
	v_add_f32_e32 v143, v143, v140
	v_add_f32_e32 v139, v139, v136
	v_add_f32_e32 v135, v135, v132
	ds_bpermute_b32 v160, v213, v163
	ds_bpermute_b32 v156, v213, v159
	ds_bpermute_b32 v152, v213, v155
	ds_bpermute_b32 v148, v213, v151
	ds_bpermute_b32 v144, v213, v147
	ds_bpermute_b32 v140, v213, v143
	ds_bpermute_b32 v136, v213, v139
	ds_bpermute_b32 v132, v213, v135
	s_waitcnt lgkmcnt(0)
	v_add_f32_e32 v163, v163, v160
	v_add_f32_e32 v159, v159, v156
	v_add_f32_e32 v155, v155, v152
	v_add_f32_e32 v151, v151, v148
	v_add_f32_e32 v147, v147, v144
	v_add_f32_e32 v143, v143, v140
	v_add_f32_e32 v139, v139, v136
	v_add_f32_e32 v135, v135, v132
	v_fmamk_f32 v163, v163, 0x3a800000, v228
	v_fmamk_f32 v159, v159, 0x3a800000, v228
	v_fmamk_f32 v155, v155, 0x3a800000, v228
	v_fmamk_f32 v151, v151, 0x3a800000, v228
	v_fmamk_f32 v147, v147, 0x3a800000, v228
	v_fmamk_f32 v143, v143, 0x3a800000, v228
	v_fmamk_f32 v139, v139, 0x3a800000, v228
	v_fmamk_f32 v135, v135, 0x3a800000, v228
	v_mov_b32_e32 v34, v163
	v_cmp_gt_f32_e32 vcc, s24, v34
	v_mul_f32_e32 v160, 0x4f800000, v34
	s_nop 0
	v_cndmask_b32_e32 v34, v34, v160, vcc
	v_sqrt_f32_e32 v160, v34
	s_nop 0
	v_add_u32_e32 v161, -1, v160
	v_fma_f32 v162, -v161, v160, v34
	v_cmp_ge_f32_e64 s[40:41], 0, v162
	v_add_u32_e32 v162, 1, v160
	s_nop 0
	v_cndmask_b32_e64 v161, v160, v161, s[40:41]
	v_fma_f32 v160, -v162, v160, v34
	v_cmp_lt_f32_e64 s[40:41], 0, v160
	s_nop 1
	v_cndmask_b32_e64 v160, v161, v162, s[40:41]
	v_mul_f32_e32 v161, 0x37800000, v160
	v_cndmask_b32_e32 v160, v160, v161, vcc
	v_cmp_class_f32_e32 vcc, v34, v229
	s_nop 1
	v_cndmask_b32_e32 v34, v160, v34, vcc
	v_div_scale_f32 v160, s[6:7], v34, v34, v211
	v_rcp_f32_e32 v161, v160
	s_nop 0
	v_fma_f32 v162, -v160, v161, 1.0
	v_fmac_f32_e32 v161, v162, v161
	v_div_scale_f32 v162, vcc, v211, v34, v211
	v_mul_f32_e32 v163, v162, v161
	v_fma_f32 v164, -v160, v163, v162
	v_fmac_f32_e32 v163, v164, v161
;     __device__ __forceinline__ void operator()(const f32x4 (&acc)[2][2][4][2], const Unit& u, int wr, int wc, int fr, int fq) const {
;     ...
;                 for (int m = 0; m < 4; ++m) part[ai][m] = *(const f32x4*)(rs + (size_t)(row0 + ai * HALF + m * 16) * 16 + 4 * fq);
; #pragma unroll
;             for (int ai = 0; ai < 2; ++ai)
; #pragma unroll
;                 for (int m = 0; m < 4; ++m) { float s = (part[ai][m][0] + part[ai][m][1]) + (part[ai][m][2] + part[ai][m][3]); s += __shfl_xor(s, 16); s += __shfl_xor(s, 32);
;                     rsv[ai][m] = sc / sqrtf(s * (1.0f / 1024.0f) + 1e-6f); }
	v_fma_f32 v160, -v160, v163, v162
	v_div_fmas_f32 v160, v160, v161, v163
	v_div_fixup_f32 v160, v160, v34, v211
	v_mov_b32_e32 v34, v159
	v_cmp_gt_f32_e32 vcc, s24, v34
	v_mul_f32_e32 v156, 0x4f800000, v34
	s_nop 0
	v_cndmask_b32_e32 v34, v34, v156, vcc
	v_sqrt_f32_e32 v156, v34
	s_nop 0
	v_add_u32_e32 v157, -1, v156
	v_fma_f32 v158, -v157, v156, v34
	v_cmp_ge_f32_e64 s[40:41], 0, v158
	v_add_u32_e32 v158, 1, v156
	s_nop 0
	v_cndmask_b32_e64 v157, v156, v157, s[40:41]
	v_fma_f32 v156, -v158, v156, v34
	v_cmp_lt_f32_e64 s[40:41], 0, v156
	s_nop 1
	v_cndmask_b32_e64 v156, v157, v158, s[40:41]
	v_mul_f32_e32 v157, 0x37800000, v156
	v_cndmask_b32_e32 v156, v156, v157, vcc
	v_cmp_class_f32_e32 vcc, v34, v229
	s_nop 1
	v_cndmask_b32_e32 v34, v156, v34, vcc
	v_div_scale_f32 v156, s[6:7], v34, v34, v211
	v_rcp_f32_e32 v157, v156
	s_nop 0
	v_fma_f32 v158, -v156, v157, 1.0
	v_fmac_f32_e32 v157, v158, v157
	v_div_scale_f32 v158, vcc, v211, v34, v211
	v_mul_f32_e32 v159, v158, v157
	v_fma_f32 v161, -v156, v159, v158
	v_fmac_f32_e32 v159, v161, v157
	v_fma_f32 v156, -v156, v159, v158
	v_div_fmas_f32 v156, v156, v157, v159
	v_div_fixup_f32 v156, v156, v34, v211
	v_pk_mul_f32 v[130:131], v[130:131], v[160:161] op_sel_hi:[1,0]
	v_pk_mul_f32 v[128:129], v[128:129], v[160:161] op_sel_hi:[1,0]
	v_pk_mul_f32 v[122:123], v[122:123], v[160:161] op_sel_hi:[1,0]
	v_pk_mul_f32 v[120:121], v[120:121], v[160:161] op_sel_hi:[1,0]
	v_mov_b32_e32 v34, v155
	v_cmp_gt_f32_e32 vcc, s24, v34
	v_mul_f32_e32 v152, 0x4f800000, v34
	s_nop 0
	v_cndmask_b32_e32 v34, v34, v152, vcc
	v_sqrt_f32_e32 v152, v34
	s_nop 0
	v_add_u32_e32 v153, -1, v152
	v_fma_f32 v154, -v153, v152, v34
	v_cmp_ge_f32_e64 s[40:41], 0, v154
	v_add_u32_e32 v154, 1, v152
	s_nop 0
	v_cndmask_b32_e64 v153, v152, v153, s[40:41]
	v_fma_f32 v152, -v154, v152, v34
	v_cmp_lt_f32_e64 s[40:41], 0, v152
	s_nop 1
	v_cndmask_b32_e64 v152, v153, v154, s[40:41]
	v_mul_f32_e32 v153, 0x37800000, v152
	v_cndmask_b32_e32 v152, v152, v153, vcc
	v_cmp_class_f32_e32 vcc, v34, v229
	s_nop 1
	v_cndmask_b32_e32 v34, v152, v34, vcc
	v_div_scale_f32 v152, s[6:7], v34, v34, v211
	v_rcp_f32_e32 v153, v152
	s_nop 0
	v_fma_f32 v154, -v152, v153, 1.0
	v_fmac_f32_e32 v153, v154, v153
	v_div_scale_f32 v154, vcc, v211, v34, v211
	v_mul_f32_e32 v155, v154, v153
	v_fma_f32 v157, -v152, v155, v154
	v_fmac_f32_e32 v155, v157, v153
	v_fma_f32 v152, -v152, v155, v154
	v_div_fmas_f32 v152, v152, v153, v155
	v_div_fixup_f32 v152, v152, v34, v211
	v_pk_mul_f32 v[116:117], v[116:117], v[156:157] op_sel_hi:[1,0]
	v_pk_mul_f32 v[106:107], v[106:107], v[156:157] op_sel_hi:[1,0]
	v_pk_mul_f32 v[104:105], v[104:105], v[156:157] op_sel_hi:[1,0]
	v_mov_b32_e32 v34, v151
	v_cmp_gt_f32_e32 vcc, s24, v34
	v_mul_f32_e32 v148, 0x4f800000, v34
	s_nop 0
	v_cndmask_b32_e32 v34, v34, v148, vcc
	v_sqrt_f32_e32 v148, v34
	s_nop 0
	v_add_u32_e32 v149, -1, v148
	v_fma_f32 v150, -v149, v148, v34
	v_cmp_ge_f32_e64 s[40:41], 0, v150
	v_add_u32_e32 v150, 1, v148
	s_nop 0
	v_cndmask_b32_e64 v149, v148, v149, s[40:41]
	v_fma_f32 v148, -v150, v148, v34
	v_cmp_lt_f32_e64 s[40:41], 0, v148
	s_nop 1
	v_cndmask_b32_e64 v148, v149, v150, s[40:41]
	v_mul_f32_e32 v149, 0x37800000, v148
	v_cndmask_b32_e32 v148, v148, v149, vcc
	v_cmp_class_f32_e32 vcc, v34, v229
	s_nop 1
	v_cndmask_b32_e32 v34, v148, v34, vcc
	v_div_scale_f32 v148, s[6:7], v34, v34, v211
	v_rcp_f32_e32 v149, v148
	s_nop 0
	v_fma_f32 v150, -v148, v149, 1.0
	v_fmac_f32_e32 v149, v150, v149
	v_div_scale_f32 v150, vcc, v211, v34, v211
	v_mul_f32_e32 v151, v150, v149
	v_fma_f32 v153, -v148, v151, v150
	v_fmac_f32_e32 v151, v153, v149
	v_fma_f32 v148, -v148, v151, v150
	v_div_fmas_f32 v148, v148, v149, v151
	v_div_fixup_f32 v148, v148, v34, v211
	v_pk_mul_f32 v[100:101], v[100:101], v[152:153] op_sel_hi:[1,0]
	v_pk_mul_f32 v[90:91], v[90:91], v[152:153] op_sel_hi:[1,0]
	v_pk_mul_f32 v[88:89], v[88:89], v[152:153] op_sel_hi:[1,0]
	v_mov_b32_e32 v34, v147
	v_cmp_gt_f32_e32 vcc, s24, v34
	v_mul_f32_e32 v144, 0x4f800000, v34
	s_nop 0
	v_cndmask_b32_e32 v34, v34, v144, vcc
	v_sqrt_f32_e32 v144, v34
	s_nop 0
	v_add_u32_e32 v145, -1, v144
	v_fma_f32 v146, -v145, v144, v34
	v_cmp_ge_f32_e64 s[40:41], 0, v146
	v_add_u32_e32 v146, 1, v144
	s_nop 0
	v_cndmask_b32_e64 v145, v144, v145, s[40:41]
	v_fma_f32 v144, -v146, v144, v34
	v_cmp_lt_f32_e64 s[40:41], 0, v144
	s_nop 1
	v_cndmask_b32_e64 v144, v145, v146, s[40:41]
	v_mul_f32_e32 v145, 0x37800000, v144
	v_cndmask_b32_e32 v144, v144, v145, vcc
	v_cmp_class_f32_e32 vcc, v34, v229
	s_nop 1
	v_cndmask_b32_e32 v34, v144, v34, vcc
	v_div_scale_f32 v144, s[6:7], v34, v34, v211
	v_rcp_f32_e32 v145, v144
	s_nop 0
	v_fma_f32 v146, -v144, v145, 1.0
	v_fmac_f32_e32 v145, v146, v145
	v_div_scale_f32 v146, vcc, v211, v34, v211
	v_mul_f32_e32 v147, v146, v145
	v_fma_f32 v149, -v144, v147, v146
	v_fmac_f32_e32 v147, v149, v145
	v_fma_f32 v144, -v144, v147, v146
	v_div_fmas_f32 v144, v144, v145, v147
	v_div_fixup_f32 v144, v144, v34, v211
	v_pk_mul_f32 v[84:85], v[84:85], v[148:149] op_sel_hi:[1,0]
	v_pk_mul_f32 v[74:75], v[74:75], v[148:149] op_sel_hi:[1,0]
	v_pk_mul_f32 v[72:73], v[72:73], v[148:149] op_sel_hi:[1,0]
	v_mov_b32_e32 v34, v143
	v_cmp_gt_f32_e32 vcc, s24, v34
	v_mul_f32_e32 v140, 0x4f800000, v34
	s_nop 0
	v_cndmask_b32_e32 v34, v34, v140, vcc
	v_sqrt_f32_e32 v140, v34
	s_nop 0
	v_add_u32_e32 v141, -1, v140
	v_fma_f32 v142, -v141, v140, v34
	v_cmp_ge_f32_e64 s[40:41], 0, v142
	v_add_u32_e32 v142, 1, v140
	s_nop 0
	v_cndmask_b32_e64 v141, v140, v141, s[40:41]
	v_fma_f32 v140, -v142, v140, v34
	v_cmp_lt_f32_e64 s[40:41], 0, v140
	s_nop 1
	v_cndmask_b32_e64 v140, v141, v142, s[40:41]
; __device__ __forceinline__ unsigned cvt_pk_bf16(float lo, float hi) { unsigned r; asm volatile("v_cvt_pk_bf16_f32 %0, %1, %2" : "=v"(r) : "v"(lo), "v"(hi)); return r; }
; __device__ __forceinline__ float fast_sigmoid(float x) { return __builtin_amdgcn_rcpf(1.0f + __builtin_amdgcn_exp2f(-x * LOG2E)); }
;     __device__ __forceinline__ void operator()(const f32x4 (&acc)[2][2][4][2], const Unit& u, int wr, int wc, int fr, int fq) const {
;     ...
;                 for (int m = 0; m < 4; ++m) part[ai][m] = *(const f32x4*)(rs + (size_t)(row0 + ai * HALF + m * 16) * 16 + 4 * fq);
; #pragma unroll
;             for (int ai = 0; ai < 2; ++ai)
; #pragma unroll
;                 for (int m = 0; m < 4; ++m) { float s = (part[ai][m][0] + part[ai][m][1]) + (part[ai][m][2] + part[ai][m][3]); s += __shfl_xor(s, 16); s += __shfl_xor(s, 32);
;                     rsv[ai][m] = sc / sqrtf(s * (1.0f / 1024.0f) + 1e-6f); }
;         } else {
; #pragma unroll
;             for (int ai = 0; ai < 2; ++ai)
; #pragma unroll
;                 for (int m = 0; m < 4; ++m) rsv[ai][m] = sc;
;         }
; #pragma unroll
;         for (int ai = 0; ai < 2; ++ai)
; #pragma unroll
;             for (int m = 0; m < 4; ++m) {
;                 const int row = row0 + ai * HALF + m * 16;
;                 const float r = rsv[ai][m];
;                 bf16_t* rowp = base + (size_t)row * ldc + col0;
; #pragma unroll
;                 for (int bj = 0; bj < 2; ++bj) {
;                     f32x4 v[2] = {acc[ai][bj][m][0] * r, acc[ai][bj][m][1] * r};
; #pragma unroll
;                     for (int n = 0; n < 2; ++n)
; #pragma unroll
;                         for (int j = 0; j < 4; ++j) {
;                             float x = v[n][j];
;                             if (MODE == 1) { x = fmaxf(x, 0.f); x = x * x; }
;                             if (MODE == 2) {
;                                 if (t == 0 || t == 3) x = x * fast_sigmoid(x);
;                                 else if (t == 1) x = lbk[bj][n][j] * __builtin_amdgcn_rcpf(1.0f + __builtin_amdgcn_exp2f(x * LOG2E));
;                             }
;                             v[n][j] = x;
;                         }
;                     u32x4 w; w.x = cvt_pk_bf16(v[0][0], v[0][1]); w.y = cvt_pk_bf16(v[0][2], v[0][3]); w.z = cvt_pk_bf16(v[1][0], v[1][1]); w.w = cvt_pk_bf16(v[1][2], v[1][3]);
;                     *(u32x4*)(rowp + bj * HALF) = w;
	v_mul_f32_e32 v141, 0x37800000, v140
	v_cndmask_b32_e32 v140, v140, v141, vcc
	v_cmp_class_f32_e32 vcc, v34, v229
	s_nop 1
	v_cndmask_b32_e32 v34, v140, v34, vcc
	v_div_scale_f32 v140, s[6:7], v34, v34, v211
	v_rcp_f32_e32 v141, v140
	s_nop 0
	v_fma_f32 v142, -v140, v141, 1.0
	v_fmac_f32_e32 v141, v142, v141
	v_div_scale_f32 v142, vcc, v211, v34, v211
	v_mul_f32_e32 v143, v142, v141
	v_fma_f32 v145, -v140, v143, v142
	v_fmac_f32_e32 v143, v145, v141
	v_fma_f32 v140, -v140, v143, v142
	v_div_fmas_f32 v140, v140, v141, v143
	v_div_fixup_f32 v140, v140, v34, v211
	v_pk_mul_f32 v[142:143], v[126:127], v[160:161] op_sel_hi:[1,0]
	v_pk_mul_f32 v[126:127], v[124:125], v[160:161] op_sel_hi:[1,0]
	v_cvt_pk_bf16_f32 v124, v128, v129
	v_cvt_pk_bf16_f32 v125, v130, v131
	v_cvt_pk_bf16_f32 v126, v126, v127
	v_cvt_pk_bf16_f32 v127, v142, v143
	v_pk_mul_f32 v[66:67], v[66:67], v[144:145] op_sel_hi:[1,0]
	v_pk_mul_f32 v[64:65], v[64:65], v[144:145] op_sel_hi:[1,0]
	v_mov_b32_e32 v34, v139
	v_cmp_gt_f32_e32 vcc, s24, v34
	v_mul_f32_e32 v136, 0x4f800000, v34
	v_pk_mul_f32 v[58:59], v[58:59], v[144:145] op_sel_hi:[1,0]
	v_cndmask_b32_e32 v34, v34, v136, vcc
	v_sqrt_f32_e32 v136, v34
	v_pk_mul_f32 v[56:57], v[56:57], v[144:145] op_sel_hi:[1,0]
	v_add_u32_e32 v137, -1, v136
	v_fma_f32 v138, -v137, v136, v34
	v_cmp_ge_f32_e64 s[40:41], 0, v138
	v_add_u32_e32 v138, 1, v136
	s_nop 0
	v_cndmask_b32_e64 v137, v136, v137, s[40:41]
	v_fma_f32 v136, -v138, v136, v34
	v_cmp_lt_f32_e64 s[40:41], 0, v136
	s_nop 1
	v_cndmask_b32_e64 v136, v137, v138, s[40:41]
	v_mul_f32_e32 v137, 0x37800000, v136
	v_cndmask_b32_e32 v136, v136, v137, vcc
	v_cmp_class_f32_e32 vcc, v34, v229
	s_nop 1
	v_cndmask_b32_e32 v34, v136, v34, vcc
	v_div_scale_f32 v136, s[6:7], v34, v34, v211
	v_rcp_f32_e32 v137, v136
	s_nop 0
	v_fma_f32 v138, -v136, v137, 1.0
	v_fmac_f32_e32 v137, v138, v137
	v_div_scale_f32 v138, vcc, v211, v34, v211
	v_mul_f32_e32 v139, v138, v137
	v_fma_f32 v141, -v136, v139, v138
	v_fmac_f32_e32 v139, v141, v137
	v_fma_f32 v136, -v136, v139, v138
	v_div_fmas_f32 v136, v136, v137, v139
	v_div_fixup_f32 v136, v136, v34, v211
	v_lshlrev_b64 v[138:139], 11, v[204:205]
	v_pk_mul_f32 v[52:53], v[52:53], v[140:141] op_sel_hi:[1,0]
	v_pk_mul_f32 v[42:43], v[42:43], v[140:141] op_sel_hi:[1,0]
	v_pk_mul_f32 v[40:41], v[40:41], v[140:141] op_sel_hi:[1,0]
	v_mov_b32_e32 v34, v135
	v_cmp_gt_f32_e32 vcc, s24, v34
	v_mul_f32_e32 v132, 0x4f800000, v34
	s_nop 0
	v_cndmask_b32_e32 v34, v34, v132, vcc
	v_sqrt_f32_e32 v132, v34
	s_nop 0
	v_add_u32_e32 v133, -1, v132
	v_fma_f32 v134, -v133, v132, v34
	v_cmp_ge_f32_e64 s[40:41], 0, v134
	v_add_u32_e32 v134, 1, v132
	s_nop 0
	v_cndmask_b32_e64 v133, v132, v133, s[40:41]
	v_fma_f32 v132, -v134, v132, v34
	v_cmp_lt_f32_e64 s[40:41], 0, v132
	s_nop 1
	v_cndmask_b32_e64 v132, v133, v134, s[40:41]
	v_mul_f32_e32 v133, 0x37800000, v132
	v_cndmask_b32_e32 v132, v132, v133, vcc
	v_cmp_class_f32_e32 vcc, v34, v229
	s_nop 1
	v_cndmask_b32_e32 v34, v132, v34, vcc
	v_div_scale_f32 v132, s[6:7], v34, v34, v211
	v_rcp_f32_e32 v133, v132
	s_nop 0
	v_fma_f32 v134, -v132, v133, 1.0
	v_fmac_f32_e32 v133, v134, v133
	v_div_scale_f32 v134, vcc, v211, v34, v211
	v_mul_f32_e32 v135, v134, v133
	v_fma_f32 v137, -v132, v135, v134
	v_fmac_f32_e32 v135, v137, v133
	v_fma_f32 v132, -v132, v135, v134
	v_or_b32_e32 v134, s1, v209
	v_div_fmas_f32 v132, v132, v133, v135
	v_ashrrev_i32_e32 v135, 31, v134
	v_lshl_add_u64 v[134:135], v[134:135], 1, s[4:5]
	v_lshl_add_u64 v[138:139], v[134:135], 0, v[138:139]
	global_store_dwordx4 v[138:139], v[124:127], off
	v_pk_mul_f32 v[36:37], v[36:37], v[136:137] op_sel_hi:[1,0]
	v_pk_mul_f32 v[22:23], v[22:23], v[136:137] op_sel_hi:[1,0]
	v_pk_mul_f32 v[124:125], v[114:115], v[160:161] op_sel_hi:[1,0]
	v_pk_mul_f32 v[114:115], v[112:113], v[160:161] op_sel_hi:[1,0]
	v_cvt_pk_bf16_f32 v112, v120, v121
	v_cvt_pk_bf16_f32 v113, v122, v123
	v_pk_mul_f32 v[20:21], v[20:21], v[136:137] op_sel_hi:[1,0]
	v_cvt_pk_bf16_f32 v114, v114, v115
	v_cvt_pk_bf16_f32 v115, v124, v125
	global_store_dwordx4 v[138:139], v[112:115], off offset:256
	v_div_fixup_f32 v132, v132, v34, v211
	v_pk_mul_f32 v[16:17], v[16:17], v[132:133] op_sel_hi:[1,0]
	v_lshlrev_b64 v[112:113], 11, v[206:207]
	v_lshl_add_u64 v[112:113], v[134:135], 0, v[112:113]
	v_pk_mul_f32 v[114:115], v[118:119], v[156:157] op_sel_hi:[1,0]
	v_pk_mul_f32 v[118:119], v[110:111], v[156:157] op_sel_hi:[1,0]
	v_pk_mul_f32 v[110:111], v[108:109], v[156:157] op_sel_hi:[1,0]
	v_cvt_pk_bf16_f32 v108, v116, v117
	v_cvt_pk_bf16_f32 v109, v114, v115
	s_mov_b64 s[4:5], -1
	v_cvt_pk_bf16_f32 v110, v110, v111
	v_cvt_pk_bf16_f32 v111, v118, v119
	global_store_dwordx4 v[112:113], v[108:111], off
	s_andn2_b64 vcc, exec, s[38:39]
	v_pk_mul_f32 v[6:7], v[6:7], v[132:133] op_sel_hi:[1,0]
	v_pk_mul_f32 v[108:109], v[98:99], v[156:157] op_sel_hi:[1,0]
	v_pk_mul_f32 v[98:99], v[96:97], v[156:157] op_sel_hi:[1,0]
	v_cvt_pk_bf16_f32 v96, v104, v105
	v_cvt_pk_bf16_f32 v97, v106, v107
; __device__ __forceinline__ unsigned cvt_pk_bf16(float lo, float hi) { unsigned r; asm volatile("v_cvt_pk_bf16_f32 %0, %1, %2" : "=v"(r) : "v"(lo), "v"(hi)); return r; }
; __device__ __forceinline__ float fast_sigmoid(float x) { return __builtin_amdgcn_rcpf(1.0f + __builtin_amdgcn_exp2f(-x * LOG2E)); }
;     __device__ __forceinline__ void operator()(const f32x4 (&acc)[2][2][4][2], const Unit& u, int wr, int wc, int fr, int fq) const {
;     ...
; #pragma unroll
;         for (int ai = 0; ai < 2; ++ai)
; #pragma unroll
;             for (int m = 0; m < 4; ++m) {
;                 const int row = row0 + ai * HALF + m * 16;
;                 const float r = rsv[ai][m];
;                 bf16_t* rowp = base + (size_t)row * ldc + col0;
; #pragma unroll
;                 for (int bj = 0; bj < 2; ++bj) {
;                     f32x4 v[2] = {acc[ai][bj][m][0] * r, acc[ai][bj][m][1] * r};
; #pragma unroll
;                     for (int n = 0; n < 2; ++n)
; #pragma unroll
;                         for (int j = 0; j < 4; ++j) {
;                             float x = v[n][j];
;                             if (MODE == 1) { x = fmaxf(x, 0.f); x = x * x; }
;                             if (MODE == 2) {
;                                 if (t == 0 || t == 3) x = x * fast_sigmoid(x);
;                                 else if (t == 1) x = lbk[bj][n][j] * __builtin_amdgcn_rcpf(1.0f + __builtin_amdgcn_exp2f(x * LOG2E));
;                             }
;                             v[n][j] = x;
;                         }
;                     u32x4 w; w.x = cvt_pk_bf16(v[0][0], v[0][1]); w.y = cvt_pk_bf16(v[0][2], v[0][3]); w.z = cvt_pk_bf16(v[1][0], v[1][1]); w.w = cvt_pk_bf16(v[1][2], v[1][3]);
;                     *(u32x4*)(rowp + bj * HALF) = w;
;                 }
;             }
	v_pk_mul_f32 v[4:5], v[4:5], v[132:133] op_sel_hi:[1,0]
	v_cvt_pk_bf16_f32 v98, v98, v99
	v_cvt_pk_bf16_f32 v99, v108, v109
	global_store_dwordx4 v[112:113], v[96:99], off offset:256
	s_nop 1
	v_lshlrev_b64 v[96:97], 11, v[202:203]
	v_lshl_add_u64 v[96:97], v[134:135], 0, v[96:97]
	v_pk_mul_f32 v[98:99], v[102:103], v[152:153] op_sel_hi:[1,0]
	v_pk_mul_f32 v[102:103], v[94:95], v[152:153] op_sel_hi:[1,0]
	v_pk_mul_f32 v[94:95], v[92:93], v[152:153] op_sel_hi:[1,0]
	v_cvt_pk_bf16_f32 v92, v100, v101
	v_cvt_pk_bf16_f32 v93, v98, v99
	s_nop 0
	v_cvt_pk_bf16_f32 v94, v94, v95
	v_cvt_pk_bf16_f32 v95, v102, v103
	global_store_dwordx4 v[96:97], v[92:95], off
	s_nop 1
	v_pk_mul_f32 v[92:93], v[82:83], v[152:153] op_sel_hi:[1,0]
	v_pk_mul_f32 v[82:83], v[80:81], v[152:153] op_sel_hi:[1,0]
	v_cvt_pk_bf16_f32 v80, v88, v89
	v_cvt_pk_bf16_f32 v81, v90, v91
	s_nop 0
	v_cvt_pk_bf16_f32 v82, v82, v83
	v_cvt_pk_bf16_f32 v83, v92, v93
	global_store_dwordx4 v[96:97], v[80:83], off offset:256
	s_nop 1
	v_lshlrev_b64 v[80:81], 11, v[200:201]
	v_lshl_add_u64 v[80:81], v[134:135], 0, v[80:81]
	v_pk_mul_f32 v[82:83], v[86:87], v[148:149] op_sel_hi:[1,0]
	v_pk_mul_f32 v[86:87], v[78:79], v[148:149] op_sel_hi:[1,0]
	v_pk_mul_f32 v[78:79], v[76:77], v[148:149] op_sel_hi:[1,0]
	v_cvt_pk_bf16_f32 v76, v84, v85
	v_cvt_pk_bf16_f32 v77, v82, v83
	s_nop 0
	v_cvt_pk_bf16_f32 v78, v78, v79
	v_cvt_pk_bf16_f32 v79, v86, v87
	global_store_dwordx4 v[80:81], v[76:79], off
	s_nop 1
	v_pk_mul_f32 v[76:77], v[70:71], v[148:149] op_sel_hi:[1,0]
	v_pk_mul_f32 v[70:71], v[68:69], v[148:149] op_sel_hi:[1,0]
	v_cvt_pk_bf16_f32 v68, v72, v73
	v_cvt_pk_bf16_f32 v69, v74, v75
	s_nop 0
	v_cvt_pk_bf16_f32 v70, v70, v71
	v_cvt_pk_bf16_f32 v71, v76, v77
	global_store_dwordx4 v[80:81], v[68:71], off offset:256
	s_nop 1
	v_lshlrev_b64 v[68:69], 11, v[198:199]
	v_lshl_add_u64 v[68:69], v[134:135], 0, v[68:69]
	v_pk_mul_f32 v[70:71], v[62:63], v[144:145] op_sel_hi:[1,0]
	v_pk_mul_f32 v[62:63], v[60:61], v[144:145] op_sel_hi:[1,0]
	v_cvt_pk_bf16_f32 v60, v64, v65
	v_cvt_pk_bf16_f32 v61, v66, v67
	s_nop 0
	v_cvt_pk_bf16_f32 v62, v62, v63
	v_cvt_pk_bf16_f32 v63, v70, v71
	global_store_dwordx4 v[68:69], v[60:63], off
	s_nop 1
	v_pk_mul_f32 v[60:61], v[50:51], v[144:145] op_sel_hi:[1,0]
	v_pk_mul_f32 v[50:51], v[48:49], v[144:145] op_sel_hi:[1,0]
	v_cvt_pk_bf16_f32 v48, v56, v57
	v_cvt_pk_bf16_f32 v49, v58, v59
	s_nop 0
	v_cvt_pk_bf16_f32 v50, v50, v51
	v_cvt_pk_bf16_f32 v51, v60, v61
	global_store_dwordx4 v[68:69], v[48:51], off offset:256
	s_nop 1
	v_lshlrev_b64 v[48:49], 11, v[196:197]
	v_lshl_add_u64 v[48:49], v[134:135], 0, v[48:49]
	v_pk_mul_f32 v[50:51], v[54:55], v[140:141] op_sel_hi:[1,0]
	v_pk_mul_f32 v[54:55], v[46:47], v[140:141] op_sel_hi:[1,0]
	v_pk_mul_f32 v[46:47], v[44:45], v[140:141] op_sel_hi:[1,0]
	v_cvt_pk_bf16_f32 v44, v52, v53
	v_cvt_pk_bf16_f32 v45, v50, v51
	s_nop 0
	v_cvt_pk_bf16_f32 v46, v46, v47
	v_cvt_pk_bf16_f32 v47, v54, v55
	global_store_dwordx4 v[48:49], v[44:47], off
	s_nop 1
	v_pk_mul_f32 v[44:45], v[30:31], v[140:141] op_sel_hi:[1,0]
	v_pk_mul_f32 v[30:31], v[28:29], v[140:141] op_sel_hi:[1,0]
	v_cvt_pk_bf16_f32 v28, v40, v41
	v_cvt_pk_bf16_f32 v29, v42, v43
	s_nop 0
	v_cvt_pk_bf16_f32 v30, v30, v31
	v_cvt_pk_bf16_f32 v31, v44, v45
	global_store_dwordx4 v[48:49], v[28:31], off offset:256
	s_nop 1
	v_lshlrev_b64 v[28:29], 11, v[194:195]
	v_lshl_add_u64 v[28:29], v[134:135], 0, v[28:29]
	v_pk_mul_f32 v[30:31], v[38:39], v[136:137] op_sel_hi:[1,0]
	v_pk_mul_f32 v[38:39], v[26:27], v[136:137] op_sel_hi:[1,0]
	v_pk_mul_f32 v[26:27], v[24:25], v[136:137] op_sel_hi:[1,0]
	v_cvt_pk_bf16_f32 v24, v36, v37
	v_cvt_pk_bf16_f32 v25, v30, v31
	s_nop 0
	v_cvt_pk_bf16_f32 v26, v26, v27
	v_cvt_pk_bf16_f32 v27, v38, v39
	global_store_dwordx4 v[28:29], v[24:27], off
	s_nop 1
	v_pk_mul_f32 v[24:25], v[14:15], v[136:137] op_sel_hi:[1,0]
	v_pk_mul_f32 v[14:15], v[12:13], v[136:137] op_sel_hi:[1,0]
	v_cvt_pk_bf16_f32 v12, v20, v21
	v_cvt_pk_bf16_f32 v13, v22, v23
	s_nop 0
	v_cvt_pk_bf16_f32 v14, v14, v15
	v_cvt_pk_bf16_f32 v15, v24, v25
	global_store_dwordx4 v[28:29], v[12:15], off offset:256
	s_nop 1
	v_lshlrev_b64 v[12:13], 11, v[192:193]
	v_lshl_add_u64 v[12:13], v[134:135], 0, v[12:13]
	v_pk_mul_f32 v[14:15], v[18:19], v[132:133] op_sel_hi:[1,0]
	v_pk_mul_f32 v[18:19], v[10:11], v[132:133] op_sel_hi:[1,0]
	v_pk_mul_f32 v[10:11], v[8:9], v[132:133] op_sel_hi:[1,0]
	v_cvt_pk_bf16_f32 v8, v16, v17
	v_cvt_pk_bf16_f32 v9, v14, v15
	s_nop 0
	v_cvt_pk_bf16_f32 v10, v10, v11
	v_cvt_pk_bf16_f32 v11, v18, v19
	global_store_dwordx4 v[12:13], v[8:11], off
	s_nop 1
	v_pk_mul_f32 v[8:9], v[2:3], v[132:133] op_sel_hi:[1,0]
	v_pk_mul_f32 v[2:3], v[0:1], v[132:133] op_sel_hi:[1,0]
	v_cvt_pk_bf16_f32 v0, v4, v5
	v_cvt_pk_bf16_f32 v1, v6, v7
	s_nop 0
	v_cvt_pk_bf16_f32 v2, v2, v3
	v_cvt_pk_bf16_f32 v3, v8, v9
	global_store_dwordx4 v[12:13], v[0:3], off offset:256
	s_cbranch_vccnz .LBB0_2150
	s_andn2_b64 vcc, exec, s[42:43]
	s_cbranch_vccnz .LBB0_2149
	s_barrier
	s_branch .LBB0_2149
